# v55 + rstd preludes of P1/P6 and P4/P9: sum-type xor-16/xor-32 ds_bpermute hops replaced by v_mov + v_permlane16/32_swap + add
# baseline (speedup 1.0000x reference)
.LBB0_223:
	v_lshl_add_u32 v164, s10, 8, v170
	v_ashrrev_i32_e32 v165, 31, v164
	v_or_b32_e32 v162, 16, v164
	v_lshlrev_b64 v[148:149], 6, v[164:165]
	v_ashrrev_i32_e32 v163, 31, v162
	v_or_b32_e32 v160, 32, v164
	v_lshl_add_u64 v[148:149], v[138:139], 0, v[148:149]
	v_lshlrev_b64 v[150:151], 6, v[162:163]
	v_ashrrev_i32_e32 v161, 31, v160
	v_or_b32_e32 v158, 48, v164
	v_lshl_add_u64 v[150:151], v[138:139], 0, v[150:151]
	global_load_dwordx4 v[166:169], v[148:149], off
	global_load_dwordx4 v[182:185], v[150:151], off
	v_lshlrev_b64 v[148:149], 6, v[160:161]
	v_ashrrev_i32_e32 v159, 31, v158
	v_lshl_add_u64 v[148:149], v[138:139], 0, v[148:149]
	v_lshlrev_b64 v[150:151], 6, v[158:159]
	v_lshl_add_u64 v[150:151], v[138:139], 0, v[150:151]
	global_load_dwordx4 v[186:189], v[148:149], off
	global_load_dwordx4 v[190:193], v[150:151], off
	v_add_u32_e32 v156, 0x80, v164
	v_ashrrev_i32_e32 v157, 31, v156
	v_lshlrev_b64 v[148:149], 6, v[156:157]
	v_add_u32_e32 v154, 0x90, v164
	v_lshl_add_u64 v[148:149], v[138:139], 0, v[148:149]
	v_ashrrev_i32_e32 v155, 31, v154
	global_load_dwordx4 v[194:197], v[148:149], off
	v_lshlrev_b64 v[148:149], 6, v[154:155]
	v_lshl_add_u64 v[148:149], v[138:139], 0, v[148:149]
	global_load_dwordx4 v[198:201], v[148:149], off
	v_and_b32_e32 v148, 64, v176
	v_xor_b32_e32 v137, 16, v176
	v_add_u32_e32 v151, 64, v148
	v_xor_b32_e32 v149, 32, v176
	v_add_u32_e32 v150, 0xa0, v164
	v_cmp_lt_i32_e32 vcc, v137, v151
	v_add_u32_e32 v148, 0xb0, v164
	s_cmp_gt_i32 s8, 7
	v_cndmask_b32_e32 v137, v176, v137, vcc
	v_cmp_lt_i32_e32 vcc, v149, v151
	v_ashrrev_i32_e32 v151, 31, v150
	v_lshlrev_b64 v[152:153], 6, v[150:151]
	v_lshl_add_u64 v[152:153], v[138:139], 0, v[152:153]
	global_load_dwordx4 v[204:207], v[152:153], off
	v_cndmask_b32_e32 v179, v176, v149, vcc
	v_ashrrev_i32_e32 v149, 31, v148
	v_lshlrev_b64 v[152:153], 6, v[148:149]
	v_lshl_add_u64 v[152:153], v[138:139], 0, v[152:153]
	global_load_dwordx4 v[208:211], v[152:153], off
	v_lshlrev_b32_e32 v180, 2, v137
	v_lshlrev_b32_e32 v179, 2, v179
	s_cselect_b64 s[10:11], -1, 0
	s_and_b64 s[50:51], s[10:11], exec
	s_cselect_b32 s20, -8, 0
	s_cselect_b32 s9, 0x8000000, 0
	s_add_i32 s20, s20, s8
	s_add_u32 s50, s58, s9
	s_addc_u32 s51, s59, 0
	s_cmp_lt_i32 s8, 8
	s_waitcnt vmcnt(0)
	v_mov_b32_e32 v152, v167
	v_mov_b32_e32 v153, v168
	v_mov_b32_e32 v167, v169
	v_pk_add_f32 v[152:153], v[152:153], v[166:167]
	v_add_f32_e32 v137, v182, v183
	v_add_f32_e32 v152, v152, v153
	v_add_f32_e32 v167, v186, v187
	v_add_f32_e32 v168, v188, v189
	v_add_f32_e32 v153, v167, v168
	v_mov_b32_e32 v168, v152
	v_add_f32_e32 v166, v184, v185
	v_add_f32_e32 v169, v190, v191
	v_add_f32_e32 v181, v192, v193
	v_add_f32_e32 v137, v137, v166
	s_waitcnt lgkmcnt(0)
	v_permlane16_swap_b32_e32 v152, v168
	v_add_f32_e32 v152, v152, v168
	v_add_f32_e32 v166, v169, v181
	v_mov_b32_e32 v181, v137
	v_mov_b32_e32 v168, v152
	v_add_f32_e32 v182, v194, v195
	v_add_f32_e32 v183, v196, v197
	v_add_f32_e32 v184, v198, v199
	s_waitcnt lgkmcnt(1)
	v_permlane16_swap_b32_e32 v137, v181
	v_add_f32_e32 v193, v137, v181
	s_waitcnt lgkmcnt(0)
	v_permlane32_swap_b32_e32 v152, v168
	v_add_f32_e32 v137, v152, v168
	v_fmamk_f32 v137, v137, 0x3a800000, v177
	v_add_f32_e32 v185, v200, v201
	v_add_f32_e32 v167, v182, v183
	v_mov_b32_e32 v182, v153
	v_add_f32_e32 v169, v184, v185
	v_mov_b32_e32 v183, v166
	v_mov_b32_e32 v184, v167
	s_waitcnt lgkmcnt(2)
	v_permlane16_swap_b32_e32 v153, v182
	v_add_f32_e32 v191, v153, v182
	v_mov_b64_e32 v[198:199], s[30:31]
	s_waitcnt lgkmcnt(1)
	v_permlane16_swap_b32_e32 v166, v183
	v_add_f32_e32 v189, v166, v183
	s_waitcnt lgkmcnt(0)
	v_permlane16_swap_b32_e32 v167, v184
	v_add_f32_e32 v187, v167, v184
	v_mov_b32_e32 v194, v193
	v_mov_b32_e32 v192, v191
	v_mov_b32_e32 v190, v189
	v_mov_b32_e32 v188, v187
	v_rsq_f32_e32 v168, v137
	s_nop 0
	v_pk_mul_f32 v[124:125], v[124:125], v[168:169] op_sel_hi:[1,0]
	v_add_f32_e32 v152, v204, v205
	v_and_b32_e32 v197, 0x7fffffff, v125
	v_and_b32_e32 v196, 0x7fffffff, v124
	v_pk_fma_f32 v[196:197], v[196:197], s[26:27], 1.0 op_sel_hi:[1,0,0]
	v_pk_mul_f32 v[204:205], v[124:125], v[124:125]
	v_rcp_f32_e32 v196, v196
	v_rcp_f32_e32 v197, v197
	v_pk_mul_f32 v[204:205], v[204:205], s[40:41] op_sel_hi:[1,0]
	v_pk_mul_f32 v[126:127], v[126:127], v[168:169] op_sel_hi:[1,0]
	v_exp_f32_e32 v204, v204
	v_pk_fma_f32 v[200:201], v[196:197], s[28:29], v[198:199] op_sel_hi:[1,0,0]
	v_exp_f32_e32 v205, v205
	v_pk_fma_f32 v[200:201], v[196:197], v[200:201], s[34:35] op_sel_hi:[1,1,0]
	v_mov_b32_e32 v137, v169
	v_add_f32_e32 v153, v206, v207
	v_pk_fma_f32 v[200:201], v[196:197], v[200:201], s[36:37] op_sel_hi:[1,1,0]
	v_and_b32_e32 v207, 0x7fffffff, v127
	v_and_b32_e32 v206, 0x7fffffff, v126
	v_pk_fma_f32 v[200:201], v[196:197], v[200:201], s[38:39] op_sel_hi:[1,1,0]
	v_pk_fma_f32 v[206:207], v[206:207], s[26:27], 1.0 op_sel_hi:[1,0,0]
	v_pk_mul_f32 v[196:197], v[196:197], v[200:201]
	v_rcp_f32_e32 v206, v206
	v_rcp_f32_e32 v207, v207
	v_pk_mul_f32 v[196:197], v[204:205], v[196:197]
	v_cmp_gt_f32_e32 vcc, 0, v124
	v_pk_mul_f32 v[204:205], v[124:125], v[196:197]
	v_pk_fma_f32 v[196:197], v[124:125], v[196:197], v[124:125] neg_lo:[1,0,0] neg_hi:[1,0,0]
	s_waitcnt lgkmcnt(0)
	v_permlane16_swap_b32_e32 v169, v137
	v_add_f32_e32 v185, v169, v137
	v_pk_mul_f32 v[200:201], v[126:127], v[126:127]
	v_cndmask_b32_e32 v137, v196, v204, vcc
	v_cmp_gt_f32_e32 vcc, 0, v125
	v_pk_mul_f32 v[122:123], v[122:123], v[168:169] op_sel_hi:[1,0]
	v_pk_mul_f32 v[120:121], v[120:121], v[168:169] op_sel_hi:[1,0]
	v_cndmask_b32_e32 v169, v197, v205, vcc
	v_pk_fma_f32 v[124:125], v[206:207], s[28:29], v[198:199] op_sel_hi:[1,0,0]
	v_pk_mul_f32 v[196:197], v[200:201], s[40:41] op_sel_hi:[1,0]
	v_pk_fma_f32 v[124:125], v[206:207], v[124:125], s[34:35] op_sel_hi:[1,1,0]
	v_exp_f32_e32 v196, v196
	v_exp_f32_e32 v197, v197
	v_pk_fma_f32 v[124:125], v[206:207], v[124:125], s[36:37] op_sel_hi:[1,1,0]
	v_and_b32_e32 v201, 0x7fffffff, v121
	v_and_b32_e32 v200, 0x7fffffff, v120
	v_pk_fma_f32 v[124:125], v[206:207], v[124:125], s[38:39] op_sel_hi:[1,1,0]
	v_pk_fma_f32 v[200:201], v[200:201], s[26:27], 1.0 op_sel_hi:[1,0,0]
	v_pk_mul_f32 v[124:125], v[206:207], v[124:125]
	v_rcp_f32_e32 v200, v200
	v_rcp_f32_e32 v201, v201
	v_pk_mul_f32 v[124:125], v[196:197], v[124:125]
	v_cmp_gt_f32_e32 vcc, 0, v126
	v_pk_mul_f32 v[196:197], v[126:127], v[124:125]
	v_pk_fma_f32 v[124:125], v[126:127], v[124:125], v[126:127] neg_lo:[1,0,0] neg_hi:[1,0,0]
	v_add_f32_e32 v166, v208, v209
	v_cndmask_b32_e32 v195, v124, v196, vcc
	v_cmp_gt_f32_e32 vcc, 0, v127
	v_pk_mul_f32 v[126:127], v[120:121], v[120:121]
	v_add_f32_e32 v167, v210, v211
	v_cndmask_b32_e32 v204, v125, v197, vcc
	v_pk_fma_f32 v[124:125], v[200:201], s[28:29], v[198:199] op_sel_hi:[1,0,0]
	v_pk_mul_f32 v[126:127], v[126:127], s[40:41] op_sel_hi:[1,0]
	v_pk_fma_f32 v[124:125], v[200:201], v[124:125], s[34:35] op_sel_hi:[1,1,0]
	v_exp_f32_e32 v126, v126
	v_pk_fma_f32 v[124:125], v[200:201], v[124:125], s[36:37] op_sel_hi:[1,1,0]
	v_exp_f32_e32 v127, v127
	v_pk_fma_f32 v[124:125], v[200:201], v[124:125], s[38:39] op_sel_hi:[1,1,0]
	v_add_f32_e32 v152, v152, v153
	v_pk_mul_f32 v[124:125], v[200:201], v[124:125]
	v_and_b32_e32 v201, 0x7fffffff, v123
	v_and_b32_e32 v200, 0x7fffffff, v122
	v_pk_fma_f32 v[200:201], v[200:201], s[26:27], 1.0 op_sel_hi:[1,0,0]
	v_pk_mul_f32 v[124:125], v[126:127], v[124:125]
	v_rcp_f32_e32 v200, v200
	v_rcp_f32_e32 v201, v201
	v_add_f32_e32 v166, v166, v167
	v_pk_mul_f32 v[126:127], v[120:121], v[124:125]
	v_pk_fma_f32 v[124:125], v[120:121], v[124:125], v[120:121] neg_lo:[1,0,0] neg_hi:[1,0,0]
	v_cmp_gt_f32_e32 vcc, 0, v120
	v_mov_b32_e32 v153, v152
	v_mov_b32_e32 v167, v166
	v_pk_mul_f32 v[196:197], v[122:123], v[122:123]
	v_cndmask_b32_e32 v126, v124, v126, vcc
	v_cmp_gt_f32_e32 vcc, 0, v121
	v_pk_fma_f32 v[120:121], v[200:201], s[28:29], v[198:199] op_sel_hi:[1,0,0]
	s_waitcnt lgkmcnt(1)
	v_permlane16_swap_b32_e32 v152, v153
	v_add_f32_e32 v183, v152, v153
	v_cndmask_b32_e32 v127, v125, v127, vcc
	v_pk_mul_f32 v[124:125], v[196:197], s[40:41] op_sel_hi:[1,0]
	v_pk_fma_f32 v[120:121], v[200:201], v[120:121], s[34:35] op_sel_hi:[1,1,0]
	v_exp_f32_e32 v124, v124
	v_exp_f32_e32 v125, v125
	v_pk_fma_f32 v[120:121], v[200:201], v[120:121], s[36:37] op_sel_hi:[1,1,0]
	s_waitcnt lgkmcnt(0)
	v_permlane16_swap_b32_e32 v166, v167
	v_add_f32_e32 v181, v166, v167
	v_pk_fma_f32 v[120:121], v[200:201], v[120:121], s[38:39] op_sel_hi:[1,1,0]
	v_mov_b32_e32 v186, v185
	v_pk_mul_f32 v[120:121], v[200:201], v[120:121]
	v_mov_b32_e32 v184, v183
	v_mov_b32_e32 v182, v181
	v_pk_mul_f32 v[120:121], v[124:125], v[120:121]
	v_lshl_or_b32 v152, s20, 8, v172
	v_pk_mul_f32 v[124:125], v[122:123], v[120:121]
	v_pk_fma_f32 v[120:121], v[122:123], v[120:121], v[122:123] neg_lo:[1,0,0] neg_hi:[1,0,0]
	v_cmp_gt_f32_e32 vcc, 0, v122
	v_ashrrev_i32_e32 v153, 31, v152
	v_lshl_add_u64 v[152:153], v[152:153], 1, s[50:51]
	v_cndmask_b32_e32 v124, v120, v124, vcc
	v_cmp_gt_f32_e32 vcc, 0, v123
	v_lshlrev_b64 v[166:167], 12, v[164:165]
	v_lshl_add_u64 v[166:167], v[152:153], 0, v[166:167]
	v_cndmask_b32_e32 v123, v121, v125, vcc
	v_cvt_pk_bf16_f32 v120, v137, v169
	v_cvt_pk_bf16_f32 v121, v195, v204
	v_cvt_pk_bf16_f32 v122, v126, v127
	v_cvt_pk_bf16_f32 v123, v124, v123
	v_mov_b32_e32 v124, 0
	v_mov_b32_e32 v125, 0
	global_store_dwordx4 v[166:167], v[120:123], off
	s_cbranch_scc1 .LBB0_225
	v_and_b32_e32 v125, 16, v120
	v_and_b32_e32 v124, 0xffff0000, v120
	v_lshlrev_b32_e32 v197, 16, v121
	v_lshlrev_b32_e32 v196, 16, v122
	v_and_b32_e32 v126, 0xffff0000, v121
	v_mov_b32_e32 v127, v124
	v_pk_mov_b32 v[204:205], v[196:197], v[124:125] op_sel:[1,0]
	v_lshlrev_b32_e32 v120, 16, v120
	v_and_b32_e32 v198, 0xffff0000, v123
	v_mov_b32_e32 v199, v126
	v_and_b32_e32 v122, 0xffff0000, v122
	v_lshlrev_b32_e32 v200, 16, v123
	v_mov_b32_e32 v123, v197
	v_mov_b32_e32 v121, v126
	v_mov_b32_e32 v201, v126
	v_pk_add_f32 v[206:207], v[126:127], v[204:205]
	v_pk_mul_f32 v[126:127], v[126:127], v[204:205]
	v_pk_add_f32 v[124:125], v[120:121], v[124:125] op_sel_hi:[0,1]
	v_mov_b32_e32 v207, v127
	v_pk_add_f32 v[126:127], v[196:197], v[122:123]
	v_pk_mul_f32 v[204:205], v[196:197], v[196:197]
	v_mov_b32_e32 v123, v198
	v_mul_f32_e32 v125, v120, v120
	v_mov_b32_e32 v127, v205
	v_pk_add_f32 v[204:205], v[198:199], v[200:201]
	v_pk_mul_f32 v[120:121], v[198:199], v[120:121]
	v_mov_b32_e32 v197, v200
	v_pk_mul_f32 v[122:123], v[122:123], v[122:123]
	v_mov_b32_e32 v205, v121
	v_pk_fma_f32 v[122:123], v[196:197], v[196:197], v[122:123]
	v_pk_add_f32 v[124:125], v[124:125], v[206:207]
	v_pk_add_f32 v[120:121], v[126:127], v[204:205]
	v_pk_add_f32 v[122:123], v[122:123], v[122:123] op_sel_hi:[0,1]
	v_pk_add_f32 v[120:121], v[124:125], v[120:121]
	v_mov_b32_e32 v137, v123
	v_pk_add_f32 v[124:125], v[120:121], v[136:137]

.LBB0_229:
	s_nop 0
	s_nop 0
	v_permlane32_swap_b32_e32 v193, v194
	v_add_f32_e32 v112, v193, v194
	v_fmamk_f32 v112, v112, 0x3a800000, v177
	v_mov_b64_e32 v[118:119], s[30:31]
	s_waitcnt lgkmcnt(1)
	s_waitcnt lgkmcnt(0)
	v_rsq_f32_e32 v114, v112
	s_nop 0
	v_pk_mul_f32 v[108:109], v[108:109], v[114:115] op_sel_hi:[1,0]
	v_pk_mul_f32 v[110:111], v[110:111], v[114:115] op_sel_hi:[1,0]
	v_and_b32_e32 v117, 0x7fffffff, v109
	v_and_b32_e32 v116, 0x7fffffff, v108
	v_pk_fma_f32 v[116:117], v[116:117], s[26:27], 1.0 op_sel_hi:[1,0,0]
	v_pk_mul_f32 v[122:123], v[108:109], v[108:109]
	v_rcp_f32_e32 v116, v116
	v_rcp_f32_e32 v117, v117
	v_pk_mul_f32 v[122:123], v[122:123], s[40:41] op_sel_hi:[1,0]
	v_and_b32_e32 v125, 0x7fffffff, v111
	v_exp_f32_e32 v122, v122
	v_pk_fma_f32 v[120:121], v[116:117], s[28:29], v[118:119] op_sel_hi:[1,0,0]
	v_exp_f32_e32 v123, v123
	v_pk_fma_f32 v[120:121], v[116:117], v[120:121], s[34:35] op_sel_hi:[1,1,0]
	v_and_b32_e32 v124, 0x7fffffff, v110
	v_pk_fma_f32 v[120:121], v[116:117], v[120:121], s[36:37] op_sel_hi:[1,1,0]
	v_pk_fma_f32 v[124:125], v[124:125], s[26:27], 1.0 op_sel_hi:[1,0,0]
	v_pk_fma_f32 v[120:121], v[116:117], v[120:121], s[38:39] op_sel_hi:[1,1,0]
	v_rcp_f32_e32 v124, v124
	v_pk_mul_f32 v[116:117], v[116:117], v[120:121]
	v_rcp_f32_e32 v125, v125
	v_pk_mul_f32 v[116:117], v[122:123], v[116:117]
	v_cmp_gt_f32_e32 vcc, 0, v108
	v_pk_mul_f32 v[122:123], v[108:109], v[116:117]
	v_pk_fma_f32 v[116:117], v[108:109], v[116:117], v[108:109] neg_lo:[1,0,0] neg_hi:[1,0,0]
	v_pk_mul_f32 v[106:107], v[106:107], v[114:115] op_sel_hi:[1,0]
	v_pk_mul_f32 v[104:105], v[104:105], v[114:115] op_sel_hi:[1,0]
	v_pk_mul_f32 v[120:121], v[110:111], v[110:111]
	v_cndmask_b32_e32 v115, v116, v122, vcc
	v_cmp_gt_f32_e32 vcc, 0, v109
	v_pk_fma_f32 v[108:109], v[124:125], s[28:29], v[118:119] op_sel_hi:[1,0,0]
	v_lshlrev_b64 v[112:113], 12, v[162:163]
	v_cndmask_b32_e32 v122, v117, v123, vcc
	v_pk_mul_f32 v[116:117], v[120:121], s[40:41] op_sel_hi:[1,0]
	v_pk_fma_f32 v[108:109], v[124:125], v[108:109], s[34:35] op_sel_hi:[1,1,0]
	v_exp_f32_e32 v116, v116
	v_exp_f32_e32 v117, v117
	v_pk_fma_f32 v[108:109], v[124:125], v[108:109], s[36:37] op_sel_hi:[1,1,0]
	v_and_b32_e32 v121, 0x7fffffff, v105
	v_and_b32_e32 v120, 0x7fffffff, v104
	v_pk_fma_f32 v[108:109], v[124:125], v[108:109], s[38:39] op_sel_hi:[1,1,0]
	v_pk_fma_f32 v[120:121], v[120:121], s[26:27], 1.0 op_sel_hi:[1,0,0]
	v_pk_mul_f32 v[108:109], v[124:125], v[108:109]
	v_rcp_f32_e32 v120, v120
	v_rcp_f32_e32 v121, v121
	v_pk_mul_f32 v[108:109], v[116:117], v[108:109]
	v_cmp_gt_f32_e32 vcc, 0, v110
	v_pk_mul_f32 v[116:117], v[110:111], v[108:109]
	v_pk_fma_f32 v[108:109], v[110:111], v[108:109], v[110:111] neg_lo:[1,0,0] neg_hi:[1,0,0]
	v_lshl_add_u64 v[112:113], v[152:153], 0, v[112:113]
	v_cndmask_b32_e32 v123, v108, v116, vcc
	v_cmp_gt_f32_e32 vcc, 0, v111
	v_pk_mul_f32 v[110:111], v[104:105], v[104:105]
	s_nop 0
	v_cndmask_b32_e32 v124, v109, v117, vcc
	v_pk_fma_f32 v[108:109], v[120:121], s[28:29], v[118:119] op_sel_hi:[1,0,0]
	v_pk_mul_f32 v[110:111], v[110:111], s[40:41] op_sel_hi:[1,0]
	v_pk_fma_f32 v[108:109], v[120:121], v[108:109], s[34:35] op_sel_hi:[1,1,0]
	v_exp_f32_e32 v110, v110
	v_pk_fma_f32 v[108:109], v[120:121], v[108:109], s[36:37] op_sel_hi:[1,1,0]
	v_exp_f32_e32 v111, v111
	v_pk_fma_f32 v[108:109], v[120:121], v[108:109], s[38:39] op_sel_hi:[1,1,0]
	v_cmp_gt_f32_e32 vcc, 0, v104
	v_pk_mul_f32 v[108:109], v[120:121], v[108:109]
	v_and_b32_e32 v121, 0x7fffffff, v107
	v_and_b32_e32 v120, 0x7fffffff, v106
	v_pk_fma_f32 v[120:121], v[120:121], s[26:27], 1.0 op_sel_hi:[1,0,0]
	v_pk_mul_f32 v[108:109], v[110:111], v[108:109]
	v_rcp_f32_e32 v120, v120
	v_rcp_f32_e32 v121, v121
	v_pk_mul_f32 v[110:111], v[104:105], v[108:109]
	v_pk_fma_f32 v[108:109], v[104:105], v[108:109], v[104:105] neg_lo:[1,0,0] neg_hi:[1,0,0]
	v_pk_mul_f32 v[116:117], v[106:107], v[106:107]
	v_cndmask_b32_e32 v110, v108, v110, vcc
	v_cmp_gt_f32_e32 vcc, 0, v105
	v_pk_fma_f32 v[104:105], v[120:121], s[28:29], v[118:119] op_sel_hi:[1,0,0]
	s_nop 0
	v_cndmask_b32_e32 v111, v109, v111, vcc
	v_pk_mul_f32 v[108:109], v[116:117], s[40:41] op_sel_hi:[1,0]
	v_pk_fma_f32 v[104:105], v[120:121], v[104:105], s[34:35] op_sel_hi:[1,1,0]
	v_exp_f32_e32 v108, v108
	v_exp_f32_e32 v109, v109
	v_pk_fma_f32 v[104:105], v[120:121], v[104:105], s[36:37] op_sel_hi:[1,1,0]
	v_cmp_gt_f32_e32 vcc, 0, v106
	v_pk_fma_f32 v[104:105], v[120:121], v[104:105], s[38:39] op_sel_hi:[1,1,0]
	s_nop 0
	v_pk_mul_f32 v[104:105], v[120:121], v[104:105]
	s_nop 0
	v_pk_mul_f32 v[104:105], v[108:109], v[104:105]
	s_nop 0
	v_pk_mul_f32 v[108:109], v[106:107], v[104:105]
	v_pk_fma_f32 v[104:105], v[106:107], v[104:105], v[106:107] neg_lo:[1,0,0] neg_hi:[1,0,0]
	s_nop 0
	v_cndmask_b32_e32 v108, v104, v108, vcc
	v_cmp_gt_f32_e32 vcc, 0, v107
	v_cvt_pk_bf16_f32 v104, v115, v122
	s_nop 1
	v_cndmask_b32_e32 v107, v105, v109, vcc
	v_cvt_pk_bf16_f32 v105, v123, v124
	v_cvt_pk_bf16_f32 v106, v110, v111
	v_cvt_pk_bf16_f32 v107, v108, v107
	v_mov_b32_e32 v108, 0
	s_and_b64 vcc, exec, s[8:9]
	v_mov_b32_e32 v109, 0
	global_store_dwordx4 v[112:113], v[104:107], off
	s_cbranch_vccnz .LBB0_231
	v_and_b32_e32 v109, 16, v104
	v_and_b32_e32 v108, 0xffff0000, v104
	v_lshlrev_b32_e32 v117, 16, v105
	v_lshlrev_b32_e32 v116, 16, v106
	v_and_b32_e32 v110, 0xffff0000, v105
	v_mov_b32_e32 v111, v108
	v_pk_mov_b32 v[122:123], v[116:117], v[108:109] op_sel:[1,0]
	v_lshlrev_b32_e32 v104, 16, v104
	v_and_b32_e32 v118, 0xffff0000, v107
	v_mov_b32_e32 v119, v110
	v_and_b32_e32 v106, 0xffff0000, v106
	v_lshlrev_b32_e32 v120, 16, v107
	v_mov_b32_e32 v107, v117
	v_mov_b32_e32 v105, v110
	v_mov_b32_e32 v121, v110
	v_pk_add_f32 v[124:125], v[110:111], v[122:123]
	v_pk_mul_f32 v[110:111], v[110:111], v[122:123]
	v_pk_add_f32 v[108:109], v[104:105], v[108:109] op_sel_hi:[0,1]
	v_mov_b32_e32 v125, v111
	v_pk_add_f32 v[110:111], v[116:117], v[106:107]
	v_pk_mul_f32 v[122:123], v[116:117], v[116:117]
	v_mov_b32_e32 v107, v118
	v_mul_f32_e32 v109, v104, v104
	v_mov_b32_e32 v111, v123
	v_pk_add_f32 v[122:123], v[118:119], v[120:121]
	v_pk_mul_f32 v[104:105], v[118:119], v[104:105]
	v_mov_b32_e32 v117, v120
	v_pk_mul_f32 v[106:107], v[106:107], v[106:107]
	v_mov_b32_e32 v123, v105
	v_pk_fma_f32 v[106:107], v[116:117], v[116:117], v[106:107]
	v_pk_add_f32 v[108:109], v[108:109], v[124:125]
	v_pk_add_f32 v[104:105], v[110:111], v[122:123]
	v_pk_add_f32 v[106:107], v[106:107], v[106:107] op_sel_hi:[0,1]
	v_pk_add_f32 v[104:105], v[108:109], v[104:105]
	v_mov_b32_e32 v137, v107
	v_pk_add_f32 v[108:109], v[104:105], v[136:137]

.LBB0_235:
	s_nop 0
	s_nop 0
	v_permlane32_swap_b32_e32 v191, v192
	v_add_f32_e32 v96, v191, v192
	v_fmamk_f32 v96, v96, 0x3a800000, v177
	v_mov_b64_e32 v[102:103], s[30:31]
	s_waitcnt lgkmcnt(1)
	s_waitcnt lgkmcnt(0)
	v_rsq_f32_e32 v98, v96
	s_nop 0
	v_pk_mul_f32 v[92:93], v[92:93], v[98:99] op_sel_hi:[1,0]
	v_pk_mul_f32 v[94:95], v[94:95], v[98:99] op_sel_hi:[1,0]
	v_and_b32_e32 v101, 0x7fffffff, v93
	v_and_b32_e32 v100, 0x7fffffff, v92
	v_pk_fma_f32 v[100:101], v[100:101], s[26:27], 1.0 op_sel_hi:[1,0,0]
	v_pk_mul_f32 v[106:107], v[92:93], v[92:93]
	v_rcp_f32_e32 v100, v100
	v_rcp_f32_e32 v101, v101
	v_pk_mul_f32 v[106:107], v[106:107], s[40:41] op_sel_hi:[1,0]
	v_and_b32_e32 v109, 0x7fffffff, v95
	v_exp_f32_e32 v106, v106
	v_pk_fma_f32 v[104:105], v[100:101], s[28:29], v[102:103] op_sel_hi:[1,0,0]
	v_exp_f32_e32 v107, v107
	v_pk_fma_f32 v[104:105], v[100:101], v[104:105], s[34:35] op_sel_hi:[1,1,0]
	v_and_b32_e32 v108, 0x7fffffff, v94
	v_pk_fma_f32 v[104:105], v[100:101], v[104:105], s[36:37] op_sel_hi:[1,1,0]
	v_pk_fma_f32 v[108:109], v[108:109], s[26:27], 1.0 op_sel_hi:[1,0,0]
	v_pk_fma_f32 v[104:105], v[100:101], v[104:105], s[38:39] op_sel_hi:[1,1,0]
	v_rcp_f32_e32 v108, v108
	v_pk_mul_f32 v[100:101], v[100:101], v[104:105]
	v_rcp_f32_e32 v109, v109
	v_pk_mul_f32 v[100:101], v[106:107], v[100:101]
	v_cmp_gt_f32_e32 vcc, 0, v92
	v_pk_mul_f32 v[106:107], v[92:93], v[100:101]
	v_pk_fma_f32 v[100:101], v[92:93], v[100:101], v[92:93] neg_lo:[1,0,0] neg_hi:[1,0,0]
	v_pk_mul_f32 v[90:91], v[90:91], v[98:99] op_sel_hi:[1,0]
	v_pk_mul_f32 v[88:89], v[88:89], v[98:99] op_sel_hi:[1,0]
	v_pk_mul_f32 v[104:105], v[94:95], v[94:95]
	v_cndmask_b32_e32 v99, v100, v106, vcc
	v_cmp_gt_f32_e32 vcc, 0, v93
	v_pk_fma_f32 v[92:93], v[108:109], s[28:29], v[102:103] op_sel_hi:[1,0,0]
	v_lshlrev_b64 v[96:97], 12, v[160:161]
	v_cndmask_b32_e32 v106, v101, v107, vcc
	v_pk_mul_f32 v[100:101], v[104:105], s[40:41] op_sel_hi:[1,0]
	v_pk_fma_f32 v[92:93], v[108:109], v[92:93], s[34:35] op_sel_hi:[1,1,0]
	v_exp_f32_e32 v100, v100
	v_exp_f32_e32 v101, v101
	v_pk_fma_f32 v[92:93], v[108:109], v[92:93], s[36:37] op_sel_hi:[1,1,0]
	v_and_b32_e32 v105, 0x7fffffff, v89
	v_and_b32_e32 v104, 0x7fffffff, v88
	v_pk_fma_f32 v[92:93], v[108:109], v[92:93], s[38:39] op_sel_hi:[1,1,0]
	v_pk_fma_f32 v[104:105], v[104:105], s[26:27], 1.0 op_sel_hi:[1,0,0]
	v_pk_mul_f32 v[92:93], v[108:109], v[92:93]
	v_rcp_f32_e32 v104, v104
	v_rcp_f32_e32 v105, v105
	v_pk_mul_f32 v[92:93], v[100:101], v[92:93]
	v_cmp_gt_f32_e32 vcc, 0, v94
	v_pk_mul_f32 v[100:101], v[94:95], v[92:93]
	v_pk_fma_f32 v[92:93], v[94:95], v[92:93], v[94:95] neg_lo:[1,0,0] neg_hi:[1,0,0]
	v_lshl_add_u64 v[96:97], v[152:153], 0, v[96:97]
	v_cndmask_b32_e32 v107, v92, v100, vcc
	v_cmp_gt_f32_e32 vcc, 0, v95
	v_pk_mul_f32 v[94:95], v[88:89], v[88:89]
	s_nop 0
	v_cndmask_b32_e32 v108, v93, v101, vcc
	v_pk_fma_f32 v[92:93], v[104:105], s[28:29], v[102:103] op_sel_hi:[1,0,0]
	v_pk_mul_f32 v[94:95], v[94:95], s[40:41] op_sel_hi:[1,0]
	v_pk_fma_f32 v[92:93], v[104:105], v[92:93], s[34:35] op_sel_hi:[1,1,0]
	v_exp_f32_e32 v94, v94
	v_pk_fma_f32 v[92:93], v[104:105], v[92:93], s[36:37] op_sel_hi:[1,1,0]
	v_exp_f32_e32 v95, v95
	v_pk_fma_f32 v[92:93], v[104:105], v[92:93], s[38:39] op_sel_hi:[1,1,0]
	v_cmp_gt_f32_e32 vcc, 0, v88
	v_pk_mul_f32 v[92:93], v[104:105], v[92:93]
	v_and_b32_e32 v105, 0x7fffffff, v91
	v_and_b32_e32 v104, 0x7fffffff, v90
	v_pk_fma_f32 v[104:105], v[104:105], s[26:27], 1.0 op_sel_hi:[1,0,0]
	v_pk_mul_f32 v[92:93], v[94:95], v[92:93]
	v_rcp_f32_e32 v104, v104
	v_rcp_f32_e32 v105, v105
	v_pk_mul_f32 v[94:95], v[88:89], v[92:93]
	v_pk_fma_f32 v[92:93], v[88:89], v[92:93], v[88:89] neg_lo:[1,0,0] neg_hi:[1,0,0]
	v_pk_mul_f32 v[100:101], v[90:91], v[90:91]
	v_cndmask_b32_e32 v94, v92, v94, vcc
	v_cmp_gt_f32_e32 vcc, 0, v89
	v_pk_fma_f32 v[88:89], v[104:105], s[28:29], v[102:103] op_sel_hi:[1,0,0]
	s_nop 0
	v_cndmask_b32_e32 v95, v93, v95, vcc
	v_pk_mul_f32 v[92:93], v[100:101], s[40:41] op_sel_hi:[1,0]
	v_pk_fma_f32 v[88:89], v[104:105], v[88:89], s[34:35] op_sel_hi:[1,1,0]
	v_exp_f32_e32 v92, v92
	v_exp_f32_e32 v93, v93
	v_pk_fma_f32 v[88:89], v[104:105], v[88:89], s[36:37] op_sel_hi:[1,1,0]
	v_cmp_gt_f32_e32 vcc, 0, v90
	v_pk_fma_f32 v[88:89], v[104:105], v[88:89], s[38:39] op_sel_hi:[1,1,0]
	s_nop 0
	v_pk_mul_f32 v[88:89], v[104:105], v[88:89]
	s_nop 0
	v_pk_mul_f32 v[88:89], v[92:93], v[88:89]
	s_nop 0
	v_pk_mul_f32 v[92:93], v[90:91], v[88:89]
	v_pk_fma_f32 v[88:89], v[90:91], v[88:89], v[90:91] neg_lo:[1,0,0] neg_hi:[1,0,0]
	s_nop 0
	v_cndmask_b32_e32 v92, v88, v92, vcc
	v_cmp_gt_f32_e32 vcc, 0, v91
	v_cvt_pk_bf16_f32 v88, v99, v106
	s_nop 1
	v_cndmask_b32_e32 v91, v89, v93, vcc
	v_cvt_pk_bf16_f32 v89, v107, v108
	v_cvt_pk_bf16_f32 v90, v94, v95
	v_cvt_pk_bf16_f32 v91, v92, v91
	v_mov_b32_e32 v92, 0
	s_and_b64 vcc, exec, s[8:9]
	v_mov_b32_e32 v93, 0
	global_store_dwordx4 v[96:97], v[88:91], off
	s_cbranch_vccnz .LBB0_237
	v_and_b32_e32 v93, 16, v88
	v_and_b32_e32 v92, 0xffff0000, v88
	v_lshlrev_b32_e32 v101, 16, v89
	v_lshlrev_b32_e32 v100, 16, v90
	v_and_b32_e32 v94, 0xffff0000, v89
	v_mov_b32_e32 v95, v92
	v_pk_mov_b32 v[106:107], v[100:101], v[92:93] op_sel:[1,0]
	v_lshlrev_b32_e32 v88, 16, v88
	v_and_b32_e32 v102, 0xffff0000, v91
	v_mov_b32_e32 v103, v94
	v_and_b32_e32 v90, 0xffff0000, v90
	v_lshlrev_b32_e32 v104, 16, v91
	v_mov_b32_e32 v91, v101
	v_mov_b32_e32 v89, v94
	v_mov_b32_e32 v105, v94
	v_pk_add_f32 v[108:109], v[94:95], v[106:107]
	v_pk_mul_f32 v[94:95], v[94:95], v[106:107]
	v_pk_add_f32 v[92:93], v[88:89], v[92:93] op_sel_hi:[0,1]
	v_mov_b32_e32 v109, v95
	v_pk_add_f32 v[94:95], v[100:101], v[90:91]
	v_pk_mul_f32 v[106:107], v[100:101], v[100:101]
	v_mov_b32_e32 v91, v102
	v_mul_f32_e32 v93, v88, v88
	v_mov_b32_e32 v95, v107
	v_pk_add_f32 v[106:107], v[102:103], v[104:105]
	v_pk_mul_f32 v[88:89], v[102:103], v[88:89]
	v_mov_b32_e32 v101, v104
	v_pk_mul_f32 v[90:91], v[90:91], v[90:91]
	v_mov_b32_e32 v107, v89
	v_pk_fma_f32 v[90:91], v[100:101], v[100:101], v[90:91]
	v_pk_add_f32 v[92:93], v[92:93], v[108:109]
	v_pk_add_f32 v[88:89], v[94:95], v[106:107]
	v_pk_add_f32 v[90:91], v[90:91], v[90:91] op_sel_hi:[0,1]
	v_pk_add_f32 v[88:89], v[92:93], v[88:89]
	v_mov_b32_e32 v137, v91
	v_pk_add_f32 v[92:93], v[88:89], v[136:137]

.LBB0_241:
	s_nop 0
	s_nop 0
	v_permlane32_swap_b32_e32 v189, v190
	v_add_f32_e32 v80, v189, v190
	v_fmamk_f32 v80, v80, 0x3a800000, v177
	v_mov_b64_e32 v[86:87], s[30:31]
	s_waitcnt lgkmcnt(1)
	s_waitcnt lgkmcnt(0)
	v_rsq_f32_e32 v82, v80
	s_nop 0
	v_pk_mul_f32 v[76:77], v[76:77], v[82:83] op_sel_hi:[1,0]
	v_pk_mul_f32 v[78:79], v[78:79], v[82:83] op_sel_hi:[1,0]
	v_and_b32_e32 v85, 0x7fffffff, v77
	v_and_b32_e32 v84, 0x7fffffff, v76
	v_pk_fma_f32 v[84:85], v[84:85], s[26:27], 1.0 op_sel_hi:[1,0,0]
	v_pk_mul_f32 v[90:91], v[76:77], v[76:77]
	v_rcp_f32_e32 v84, v84
	v_rcp_f32_e32 v85, v85
	v_pk_mul_f32 v[90:91], v[90:91], s[40:41] op_sel_hi:[1,0]
	v_and_b32_e32 v93, 0x7fffffff, v79
	v_exp_f32_e32 v90, v90
	v_pk_fma_f32 v[88:89], v[84:85], s[28:29], v[86:87] op_sel_hi:[1,0,0]
	v_exp_f32_e32 v91, v91
	v_pk_fma_f32 v[88:89], v[84:85], v[88:89], s[34:35] op_sel_hi:[1,1,0]
	v_and_b32_e32 v92, 0x7fffffff, v78
	v_pk_fma_f32 v[88:89], v[84:85], v[88:89], s[36:37] op_sel_hi:[1,1,0]
	v_pk_fma_f32 v[92:93], v[92:93], s[26:27], 1.0 op_sel_hi:[1,0,0]
	v_pk_fma_f32 v[88:89], v[84:85], v[88:89], s[38:39] op_sel_hi:[1,1,0]
	v_rcp_f32_e32 v92, v92
	v_pk_mul_f32 v[84:85], v[84:85], v[88:89]
	v_rcp_f32_e32 v93, v93
	v_pk_mul_f32 v[84:85], v[90:91], v[84:85]
	v_cmp_gt_f32_e32 vcc, 0, v76
	v_pk_mul_f32 v[90:91], v[76:77], v[84:85]
	v_pk_fma_f32 v[84:85], v[76:77], v[84:85], v[76:77] neg_lo:[1,0,0] neg_hi:[1,0,0]
	v_pk_mul_f32 v[74:75], v[74:75], v[82:83] op_sel_hi:[1,0]
	v_pk_mul_f32 v[72:73], v[72:73], v[82:83] op_sel_hi:[1,0]
	v_pk_mul_f32 v[88:89], v[78:79], v[78:79]
	v_cndmask_b32_e32 v83, v84, v90, vcc
	v_cmp_gt_f32_e32 vcc, 0, v77
	v_pk_fma_f32 v[76:77], v[92:93], s[28:29], v[86:87] op_sel_hi:[1,0,0]
	v_lshlrev_b64 v[80:81], 12, v[158:159]
	v_cndmask_b32_e32 v90, v85, v91, vcc
	v_pk_mul_f32 v[84:85], v[88:89], s[40:41] op_sel_hi:[1,0]
	v_pk_fma_f32 v[76:77], v[92:93], v[76:77], s[34:35] op_sel_hi:[1,1,0]
	v_exp_f32_e32 v84, v84
	v_exp_f32_e32 v85, v85
	v_pk_fma_f32 v[76:77], v[92:93], v[76:77], s[36:37] op_sel_hi:[1,1,0]
	v_and_b32_e32 v89, 0x7fffffff, v73
	v_and_b32_e32 v88, 0x7fffffff, v72
	v_pk_fma_f32 v[76:77], v[92:93], v[76:77], s[38:39] op_sel_hi:[1,1,0]
	v_pk_fma_f32 v[88:89], v[88:89], s[26:27], 1.0 op_sel_hi:[1,0,0]
	v_pk_mul_f32 v[76:77], v[92:93], v[76:77]
	v_rcp_f32_e32 v88, v88
	v_rcp_f32_e32 v89, v89
	v_pk_mul_f32 v[76:77], v[84:85], v[76:77]
	v_cmp_gt_f32_e32 vcc, 0, v78
	v_pk_mul_f32 v[84:85], v[78:79], v[76:77]
	v_pk_fma_f32 v[76:77], v[78:79], v[76:77], v[78:79] neg_lo:[1,0,0] neg_hi:[1,0,0]
	v_lshl_add_u64 v[80:81], v[152:153], 0, v[80:81]
	v_cndmask_b32_e32 v91, v76, v84, vcc
	v_cmp_gt_f32_e32 vcc, 0, v79
	v_pk_mul_f32 v[78:79], v[72:73], v[72:73]
	s_nop 0
	v_cndmask_b32_e32 v92, v77, v85, vcc
	v_pk_fma_f32 v[76:77], v[88:89], s[28:29], v[86:87] op_sel_hi:[1,0,0]
	v_pk_mul_f32 v[78:79], v[78:79], s[40:41] op_sel_hi:[1,0]
	v_pk_fma_f32 v[76:77], v[88:89], v[76:77], s[34:35] op_sel_hi:[1,1,0]
	v_exp_f32_e32 v78, v78
	v_pk_fma_f32 v[76:77], v[88:89], v[76:77], s[36:37] op_sel_hi:[1,1,0]
	v_exp_f32_e32 v79, v79
	v_pk_fma_f32 v[76:77], v[88:89], v[76:77], s[38:39] op_sel_hi:[1,1,0]
	v_cmp_gt_f32_e32 vcc, 0, v72
	v_pk_mul_f32 v[76:77], v[88:89], v[76:77]
	v_and_b32_e32 v89, 0x7fffffff, v75
	v_and_b32_e32 v88, 0x7fffffff, v74
	v_pk_fma_f32 v[88:89], v[88:89], s[26:27], 1.0 op_sel_hi:[1,0,0]
	v_pk_mul_f32 v[76:77], v[78:79], v[76:77]
	v_rcp_f32_e32 v88, v88
	v_rcp_f32_e32 v89, v89
	v_pk_mul_f32 v[78:79], v[72:73], v[76:77]
	v_pk_fma_f32 v[76:77], v[72:73], v[76:77], v[72:73] neg_lo:[1,0,0] neg_hi:[1,0,0]
	v_pk_mul_f32 v[84:85], v[74:75], v[74:75]
	v_cndmask_b32_e32 v78, v76, v78, vcc
	v_cmp_gt_f32_e32 vcc, 0, v73
	v_pk_fma_f32 v[72:73], v[88:89], s[28:29], v[86:87] op_sel_hi:[1,0,0]
	s_nop 0
	v_cndmask_b32_e32 v79, v77, v79, vcc
	v_pk_mul_f32 v[76:77], v[84:85], s[40:41] op_sel_hi:[1,0]
	v_pk_fma_f32 v[72:73], v[88:89], v[72:73], s[34:35] op_sel_hi:[1,1,0]
	v_exp_f32_e32 v76, v76
	v_exp_f32_e32 v77, v77
	v_pk_fma_f32 v[72:73], v[88:89], v[72:73], s[36:37] op_sel_hi:[1,1,0]
	v_cmp_gt_f32_e32 vcc, 0, v74
	v_pk_fma_f32 v[72:73], v[88:89], v[72:73], s[38:39] op_sel_hi:[1,1,0]
	s_nop 0
	v_pk_mul_f32 v[72:73], v[88:89], v[72:73]
	s_nop 0
	v_pk_mul_f32 v[72:73], v[76:77], v[72:73]
	s_nop 0
	v_pk_mul_f32 v[76:77], v[74:75], v[72:73]
	v_pk_fma_f32 v[72:73], v[74:75], v[72:73], v[74:75] neg_lo:[1,0,0] neg_hi:[1,0,0]
	s_nop 0
	v_cndmask_b32_e32 v76, v72, v76, vcc
	v_cmp_gt_f32_e32 vcc, 0, v75
	v_cvt_pk_bf16_f32 v72, v83, v90
	s_nop 1
	v_cndmask_b32_e32 v75, v73, v77, vcc
	v_cvt_pk_bf16_f32 v73, v91, v92
	v_cvt_pk_bf16_f32 v74, v78, v79
	v_cvt_pk_bf16_f32 v75, v76, v75
	v_mov_b32_e32 v76, 0
	s_and_b64 vcc, exec, s[8:9]
	v_mov_b32_e32 v77, 0
	global_store_dwordx4 v[80:81], v[72:75], off
	s_cbranch_vccnz .LBB0_243
	v_and_b32_e32 v77, 16, v72
	v_and_b32_e32 v76, 0xffff0000, v72
	v_lshlrev_b32_e32 v85, 16, v73
	v_lshlrev_b32_e32 v84, 16, v74
	v_and_b32_e32 v78, 0xffff0000, v73
	v_mov_b32_e32 v79, v76
	v_pk_mov_b32 v[90:91], v[84:85], v[76:77] op_sel:[1,0]
	v_lshlrev_b32_e32 v72, 16, v72
	v_and_b32_e32 v86, 0xffff0000, v75
	v_mov_b32_e32 v87, v78
	v_and_b32_e32 v74, 0xffff0000, v74
	v_lshlrev_b32_e32 v88, 16, v75
	v_mov_b32_e32 v75, v85
	v_mov_b32_e32 v73, v78
	v_mov_b32_e32 v89, v78
	v_pk_add_f32 v[92:93], v[78:79], v[90:91]
	v_pk_mul_f32 v[78:79], v[78:79], v[90:91]
	v_pk_add_f32 v[76:77], v[72:73], v[76:77] op_sel_hi:[0,1]
	v_mov_b32_e32 v93, v79
	v_pk_add_f32 v[78:79], v[84:85], v[74:75]
	v_pk_mul_f32 v[90:91], v[84:85], v[84:85]
	v_mov_b32_e32 v75, v86
	v_mul_f32_e32 v77, v72, v72
	v_mov_b32_e32 v79, v91
	v_pk_add_f32 v[90:91], v[86:87], v[88:89]
	v_pk_mul_f32 v[72:73], v[86:87], v[72:73]
	v_mov_b32_e32 v85, v88
	v_pk_mul_f32 v[74:75], v[74:75], v[74:75]
	v_mov_b32_e32 v91, v73
	v_pk_fma_f32 v[74:75], v[84:85], v[84:85], v[74:75]
	v_pk_add_f32 v[76:77], v[76:77], v[92:93]
	v_pk_add_f32 v[72:73], v[78:79], v[90:91]
	v_pk_add_f32 v[74:75], v[74:75], v[74:75] op_sel_hi:[0,1]
	v_pk_add_f32 v[72:73], v[76:77], v[72:73]
	v_mov_b32_e32 v137, v75
	v_pk_add_f32 v[76:77], v[72:73], v[136:137]

.LBB0_247:
	s_nop 0
	s_nop 0
	v_permlane32_swap_b32_e32 v187, v188
	v_add_f32_e32 v64, v187, v188
	v_fmamk_f32 v64, v64, 0x3a800000, v177
	v_mov_b64_e32 v[70:71], s[30:31]
	s_waitcnt lgkmcnt(1)
	s_waitcnt lgkmcnt(0)
	v_rsq_f32_e32 v66, v64
	s_nop 0
	v_pk_mul_f32 v[60:61], v[60:61], v[66:67] op_sel_hi:[1,0]
	v_pk_mul_f32 v[62:63], v[62:63], v[66:67] op_sel_hi:[1,0]
	v_and_b32_e32 v69, 0x7fffffff, v61
	v_and_b32_e32 v68, 0x7fffffff, v60
	v_pk_fma_f32 v[68:69], v[68:69], s[26:27], 1.0 op_sel_hi:[1,0,0]
	v_pk_mul_f32 v[74:75], v[60:61], v[60:61]
	v_rcp_f32_e32 v68, v68
	v_rcp_f32_e32 v69, v69
	v_pk_mul_f32 v[74:75], v[74:75], s[40:41] op_sel_hi:[1,0]
	v_and_b32_e32 v77, 0x7fffffff, v63
	v_exp_f32_e32 v74, v74
	v_pk_fma_f32 v[72:73], v[68:69], s[28:29], v[70:71] op_sel_hi:[1,0,0]
	v_exp_f32_e32 v75, v75
	v_pk_fma_f32 v[72:73], v[68:69], v[72:73], s[34:35] op_sel_hi:[1,1,0]
	v_and_b32_e32 v76, 0x7fffffff, v62
	v_pk_fma_f32 v[72:73], v[68:69], v[72:73], s[36:37] op_sel_hi:[1,1,0]
	v_pk_fma_f32 v[76:77], v[76:77], s[26:27], 1.0 op_sel_hi:[1,0,0]
	v_pk_fma_f32 v[72:73], v[68:69], v[72:73], s[38:39] op_sel_hi:[1,1,0]
	v_rcp_f32_e32 v76, v76
	v_pk_mul_f32 v[68:69], v[68:69], v[72:73]
	v_rcp_f32_e32 v77, v77
	v_pk_mul_f32 v[68:69], v[74:75], v[68:69]
	v_cmp_gt_f32_e32 vcc, 0, v60
	v_pk_mul_f32 v[74:75], v[60:61], v[68:69]
	v_pk_fma_f32 v[68:69], v[60:61], v[68:69], v[60:61] neg_lo:[1,0,0] neg_hi:[1,0,0]
	v_pk_mul_f32 v[58:59], v[58:59], v[66:67] op_sel_hi:[1,0]
	v_pk_mul_f32 v[56:57], v[56:57], v[66:67] op_sel_hi:[1,0]
	v_pk_mul_f32 v[72:73], v[62:63], v[62:63]
	v_cndmask_b32_e32 v67, v68, v74, vcc
	v_cmp_gt_f32_e32 vcc, 0, v61
	v_pk_fma_f32 v[60:61], v[76:77], s[28:29], v[70:71] op_sel_hi:[1,0,0]
	v_lshlrev_b64 v[64:65], 12, v[156:157]
	v_cndmask_b32_e32 v74, v69, v75, vcc
	v_pk_mul_f32 v[68:69], v[72:73], s[40:41] op_sel_hi:[1,0]
	v_pk_fma_f32 v[60:61], v[76:77], v[60:61], s[34:35] op_sel_hi:[1,1,0]
	v_exp_f32_e32 v68, v68
	v_exp_f32_e32 v69, v69
	v_pk_fma_f32 v[60:61], v[76:77], v[60:61], s[36:37] op_sel_hi:[1,1,0]
	v_and_b32_e32 v73, 0x7fffffff, v57
	v_and_b32_e32 v72, 0x7fffffff, v56
	v_pk_fma_f32 v[60:61], v[76:77], v[60:61], s[38:39] op_sel_hi:[1,1,0]
	v_pk_fma_f32 v[72:73], v[72:73], s[26:27], 1.0 op_sel_hi:[1,0,0]
	v_pk_mul_f32 v[60:61], v[76:77], v[60:61]
	v_rcp_f32_e32 v72, v72
	v_rcp_f32_e32 v73, v73
	v_pk_mul_f32 v[60:61], v[68:69], v[60:61]
	v_cmp_gt_f32_e32 vcc, 0, v62
	v_pk_mul_f32 v[68:69], v[62:63], v[60:61]
	v_pk_fma_f32 v[60:61], v[62:63], v[60:61], v[62:63] neg_lo:[1,0,0] neg_hi:[1,0,0]
	v_lshl_add_u64 v[64:65], v[152:153], 0, v[64:65]
	v_cndmask_b32_e32 v75, v60, v68, vcc
	v_cmp_gt_f32_e32 vcc, 0, v63
	v_pk_mul_f32 v[62:63], v[56:57], v[56:57]
	s_nop 0
	v_cndmask_b32_e32 v76, v61, v69, vcc
	v_pk_fma_f32 v[60:61], v[72:73], s[28:29], v[70:71] op_sel_hi:[1,0,0]
	v_pk_mul_f32 v[62:63], v[62:63], s[40:41] op_sel_hi:[1,0]
	v_pk_fma_f32 v[60:61], v[72:73], v[60:61], s[34:35] op_sel_hi:[1,1,0]
	v_exp_f32_e32 v62, v62
	v_pk_fma_f32 v[60:61], v[72:73], v[60:61], s[36:37] op_sel_hi:[1,1,0]
	v_exp_f32_e32 v63, v63
	v_pk_fma_f32 v[60:61], v[72:73], v[60:61], s[38:39] op_sel_hi:[1,1,0]
	v_cmp_gt_f32_e32 vcc, 0, v56
	v_pk_mul_f32 v[60:61], v[72:73], v[60:61]
	v_and_b32_e32 v73, 0x7fffffff, v59
	v_and_b32_e32 v72, 0x7fffffff, v58
	v_pk_fma_f32 v[72:73], v[72:73], s[26:27], 1.0 op_sel_hi:[1,0,0]
	v_pk_mul_f32 v[60:61], v[62:63], v[60:61]
	v_rcp_f32_e32 v72, v72
	v_rcp_f32_e32 v73, v73
	v_pk_mul_f32 v[62:63], v[56:57], v[60:61]
	v_pk_fma_f32 v[60:61], v[56:57], v[60:61], v[56:57] neg_lo:[1,0,0] neg_hi:[1,0,0]
	v_pk_mul_f32 v[68:69], v[58:59], v[58:59]
	v_cndmask_b32_e32 v62, v60, v62, vcc
	v_cmp_gt_f32_e32 vcc, 0, v57
	v_pk_fma_f32 v[56:57], v[72:73], s[28:29], v[70:71] op_sel_hi:[1,0,0]
	s_nop 0
	v_cndmask_b32_e32 v63, v61, v63, vcc
	v_pk_mul_f32 v[60:61], v[68:69], s[40:41] op_sel_hi:[1,0]
	v_pk_fma_f32 v[56:57], v[72:73], v[56:57], s[34:35] op_sel_hi:[1,1,0]
	v_exp_f32_e32 v60, v60
	v_exp_f32_e32 v61, v61
	v_pk_fma_f32 v[56:57], v[72:73], v[56:57], s[36:37] op_sel_hi:[1,1,0]
	v_cmp_gt_f32_e32 vcc, 0, v58
	v_pk_fma_f32 v[56:57], v[72:73], v[56:57], s[38:39] op_sel_hi:[1,1,0]
	s_nop 0
	v_pk_mul_f32 v[56:57], v[72:73], v[56:57]
	s_nop 0
	v_pk_mul_f32 v[56:57], v[60:61], v[56:57]
	s_nop 0
	v_pk_mul_f32 v[60:61], v[58:59], v[56:57]
	v_pk_fma_f32 v[56:57], v[58:59], v[56:57], v[58:59] neg_lo:[1,0,0] neg_hi:[1,0,0]
	s_nop 0
	v_cndmask_b32_e32 v60, v56, v60, vcc
	v_cmp_gt_f32_e32 vcc, 0, v59
	v_cvt_pk_bf16_f32 v56, v67, v74
	s_nop 1
	v_cndmask_b32_e32 v59, v57, v61, vcc
	v_cvt_pk_bf16_f32 v57, v75, v76
	v_cvt_pk_bf16_f32 v58, v62, v63
	v_cvt_pk_bf16_f32 v59, v60, v59
	v_mov_b32_e32 v60, 0
	s_and_b64 vcc, exec, s[8:9]
	v_mov_b32_e32 v61, 0
	global_store_dwordx4 v[64:65], v[56:59], off
	s_cbranch_vccnz .LBB0_249
	v_and_b32_e32 v61, 16, v56
	v_and_b32_e32 v60, 0xffff0000, v56
	v_lshlrev_b32_e32 v69, 16, v57
	v_lshlrev_b32_e32 v68, 16, v58
	v_and_b32_e32 v62, 0xffff0000, v57
	v_mov_b32_e32 v63, v60
	v_pk_mov_b32 v[74:75], v[68:69], v[60:61] op_sel:[1,0]
	v_lshlrev_b32_e32 v56, 16, v56
	v_and_b32_e32 v70, 0xffff0000, v59
	v_mov_b32_e32 v71, v62
	v_and_b32_e32 v58, 0xffff0000, v58
	v_lshlrev_b32_e32 v72, 16, v59
	v_mov_b32_e32 v59, v69
	v_mov_b32_e32 v57, v62
	v_mov_b32_e32 v73, v62
	v_pk_add_f32 v[76:77], v[62:63], v[74:75]
	v_pk_mul_f32 v[62:63], v[62:63], v[74:75]
	v_pk_add_f32 v[60:61], v[56:57], v[60:61] op_sel_hi:[0,1]
	v_mov_b32_e32 v77, v63
	v_pk_add_f32 v[62:63], v[68:69], v[58:59]
	v_pk_mul_f32 v[74:75], v[68:69], v[68:69]
	v_mov_b32_e32 v59, v70
	v_mul_f32_e32 v61, v56, v56
	v_mov_b32_e32 v63, v75
	v_pk_add_f32 v[74:75], v[70:71], v[72:73]
	v_pk_mul_f32 v[56:57], v[70:71], v[56:57]
	v_mov_b32_e32 v69, v72
	v_pk_mul_f32 v[58:59], v[58:59], v[58:59]
	v_mov_b32_e32 v75, v57
	v_pk_fma_f32 v[58:59], v[68:69], v[68:69], v[58:59]
	v_pk_add_f32 v[60:61], v[60:61], v[76:77]
	v_pk_add_f32 v[56:57], v[62:63], v[74:75]
	v_pk_add_f32 v[58:59], v[58:59], v[58:59] op_sel_hi:[0,1]
	v_pk_add_f32 v[56:57], v[60:61], v[56:57]
	v_mov_b32_e32 v137, v59
	v_pk_add_f32 v[60:61], v[56:57], v[136:137]

.LBB0_253:
	s_nop 0
	s_nop 0
	v_permlane32_swap_b32_e32 v185, v186
	v_add_f32_e32 v48, v185, v186
	v_fmamk_f32 v48, v48, 0x3a800000, v177
	v_mov_b64_e32 v[54:55], s[30:31]
	s_waitcnt lgkmcnt(1)
	s_waitcnt lgkmcnt(0)
	v_rsq_f32_e32 v50, v48
	s_nop 0
	v_pk_mul_f32 v[44:45], v[44:45], v[50:51] op_sel_hi:[1,0]
	v_pk_mul_f32 v[46:47], v[46:47], v[50:51] op_sel_hi:[1,0]
	v_and_b32_e32 v53, 0x7fffffff, v45
	v_and_b32_e32 v52, 0x7fffffff, v44
	v_pk_fma_f32 v[52:53], v[52:53], s[26:27], 1.0 op_sel_hi:[1,0,0]
	v_pk_mul_f32 v[58:59], v[44:45], v[44:45]
	v_rcp_f32_e32 v52, v52
	v_rcp_f32_e32 v53, v53
	v_pk_mul_f32 v[58:59], v[58:59], s[40:41] op_sel_hi:[1,0]
	v_and_b32_e32 v61, 0x7fffffff, v47
	v_exp_f32_e32 v58, v58
	v_pk_fma_f32 v[56:57], v[52:53], s[28:29], v[54:55] op_sel_hi:[1,0,0]
	v_exp_f32_e32 v59, v59
	v_pk_fma_f32 v[56:57], v[52:53], v[56:57], s[34:35] op_sel_hi:[1,1,0]
	v_and_b32_e32 v60, 0x7fffffff, v46
	v_pk_fma_f32 v[56:57], v[52:53], v[56:57], s[36:37] op_sel_hi:[1,1,0]
	v_pk_fma_f32 v[60:61], v[60:61], s[26:27], 1.0 op_sel_hi:[1,0,0]
	v_pk_fma_f32 v[56:57], v[52:53], v[56:57], s[38:39] op_sel_hi:[1,1,0]
	v_rcp_f32_e32 v60, v60
	v_pk_mul_f32 v[52:53], v[52:53], v[56:57]
	v_rcp_f32_e32 v61, v61
	v_pk_mul_f32 v[52:53], v[58:59], v[52:53]
	v_cmp_gt_f32_e32 vcc, 0, v44
	v_pk_mul_f32 v[58:59], v[44:45], v[52:53]
	v_pk_fma_f32 v[52:53], v[44:45], v[52:53], v[44:45] neg_lo:[1,0,0] neg_hi:[1,0,0]
	v_pk_mul_f32 v[42:43], v[42:43], v[50:51] op_sel_hi:[1,0]
	v_pk_mul_f32 v[40:41], v[40:41], v[50:51] op_sel_hi:[1,0]
	v_pk_mul_f32 v[56:57], v[46:47], v[46:47]
	v_cndmask_b32_e32 v51, v52, v58, vcc
	v_cmp_gt_f32_e32 vcc, 0, v45
	v_pk_fma_f32 v[44:45], v[60:61], s[28:29], v[54:55] op_sel_hi:[1,0,0]
	v_lshlrev_b64 v[48:49], 12, v[154:155]
	v_cndmask_b32_e32 v58, v53, v59, vcc
	v_pk_mul_f32 v[52:53], v[56:57], s[40:41] op_sel_hi:[1,0]
	v_pk_fma_f32 v[44:45], v[60:61], v[44:45], s[34:35] op_sel_hi:[1,1,0]
	v_exp_f32_e32 v52, v52
	v_exp_f32_e32 v53, v53
	v_pk_fma_f32 v[44:45], v[60:61], v[44:45], s[36:37] op_sel_hi:[1,1,0]
	v_and_b32_e32 v57, 0x7fffffff, v41
	v_and_b32_e32 v56, 0x7fffffff, v40
	v_pk_fma_f32 v[44:45], v[60:61], v[44:45], s[38:39] op_sel_hi:[1,1,0]
	v_pk_fma_f32 v[56:57], v[56:57], s[26:27], 1.0 op_sel_hi:[1,0,0]
	v_pk_mul_f32 v[44:45], v[60:61], v[44:45]
	v_rcp_f32_e32 v56, v56
	v_rcp_f32_e32 v57, v57
	v_pk_mul_f32 v[44:45], v[52:53], v[44:45]
	v_cmp_gt_f32_e32 vcc, 0, v46
	v_pk_mul_f32 v[52:53], v[46:47], v[44:45]
	v_pk_fma_f32 v[44:45], v[46:47], v[44:45], v[46:47] neg_lo:[1,0,0] neg_hi:[1,0,0]
	v_lshl_add_u64 v[48:49], v[152:153], 0, v[48:49]
	v_cndmask_b32_e32 v59, v44, v52, vcc
	v_cmp_gt_f32_e32 vcc, 0, v47
	v_pk_mul_f32 v[46:47], v[40:41], v[40:41]
	s_nop 0
	v_cndmask_b32_e32 v60, v45, v53, vcc
	v_pk_fma_f32 v[44:45], v[56:57], s[28:29], v[54:55] op_sel_hi:[1,0,0]
	v_pk_mul_f32 v[46:47], v[46:47], s[40:41] op_sel_hi:[1,0]
	v_pk_fma_f32 v[44:45], v[56:57], v[44:45], s[34:35] op_sel_hi:[1,1,0]
	v_exp_f32_e32 v46, v46
	v_pk_fma_f32 v[44:45], v[56:57], v[44:45], s[36:37] op_sel_hi:[1,1,0]
	v_exp_f32_e32 v47, v47
	v_pk_fma_f32 v[44:45], v[56:57], v[44:45], s[38:39] op_sel_hi:[1,1,0]
	v_cmp_gt_f32_e32 vcc, 0, v40
	v_pk_mul_f32 v[44:45], v[56:57], v[44:45]
	v_and_b32_e32 v57, 0x7fffffff, v43
	v_and_b32_e32 v56, 0x7fffffff, v42
	v_pk_fma_f32 v[56:57], v[56:57], s[26:27], 1.0 op_sel_hi:[1,0,0]
	v_pk_mul_f32 v[44:45], v[46:47], v[44:45]
	v_rcp_f32_e32 v56, v56
	v_rcp_f32_e32 v57, v57
	v_pk_mul_f32 v[46:47], v[40:41], v[44:45]
	v_pk_fma_f32 v[44:45], v[40:41], v[44:45], v[40:41] neg_lo:[1,0,0] neg_hi:[1,0,0]
	v_pk_mul_f32 v[52:53], v[42:43], v[42:43]
	v_cndmask_b32_e32 v46, v44, v46, vcc
	v_cmp_gt_f32_e32 vcc, 0, v41
	v_pk_fma_f32 v[40:41], v[56:57], s[28:29], v[54:55] op_sel_hi:[1,0,0]
	s_nop 0
	v_cndmask_b32_e32 v47, v45, v47, vcc
	v_pk_mul_f32 v[44:45], v[52:53], s[40:41] op_sel_hi:[1,0]
	v_pk_fma_f32 v[40:41], v[56:57], v[40:41], s[34:35] op_sel_hi:[1,1,0]
	v_exp_f32_e32 v44, v44
	v_exp_f32_e32 v45, v45
	v_pk_fma_f32 v[40:41], v[56:57], v[40:41], s[36:37] op_sel_hi:[1,1,0]
	v_cmp_gt_f32_e32 vcc, 0, v42
	v_pk_fma_f32 v[40:41], v[56:57], v[40:41], s[38:39] op_sel_hi:[1,1,0]
	s_nop 0
	v_pk_mul_f32 v[40:41], v[56:57], v[40:41]
	s_nop 0
	v_pk_mul_f32 v[40:41], v[44:45], v[40:41]
	s_nop 0
	v_pk_mul_f32 v[44:45], v[42:43], v[40:41]
	v_pk_fma_f32 v[40:41], v[42:43], v[40:41], v[42:43] neg_lo:[1,0,0] neg_hi:[1,0,0]
	s_nop 0
	v_cndmask_b32_e32 v44, v40, v44, vcc
	v_cmp_gt_f32_e32 vcc, 0, v43
	v_cvt_pk_bf16_f32 v40, v51, v58
	s_nop 1
	v_cndmask_b32_e32 v43, v41, v45, vcc
	v_cvt_pk_bf16_f32 v41, v59, v60
	v_cvt_pk_bf16_f32 v42, v46, v47
	v_cvt_pk_bf16_f32 v43, v44, v43
	v_mov_b32_e32 v44, 0
	s_and_b64 vcc, exec, s[8:9]
	v_mov_b32_e32 v45, 0
	global_store_dwordx4 v[48:49], v[40:43], off
	s_cbranch_vccnz .LBB0_255
	v_and_b32_e32 v45, 16, v40
	v_and_b32_e32 v44, 0xffff0000, v40
	v_lshlrev_b32_e32 v53, 16, v41
	v_lshlrev_b32_e32 v52, 16, v42
	v_and_b32_e32 v46, 0xffff0000, v41
	v_mov_b32_e32 v47, v44
	v_pk_mov_b32 v[58:59], v[52:53], v[44:45] op_sel:[1,0]
	v_lshlrev_b32_e32 v40, 16, v40
	v_and_b32_e32 v54, 0xffff0000, v43
	v_mov_b32_e32 v55, v46
	v_and_b32_e32 v42, 0xffff0000, v42
	v_lshlrev_b32_e32 v56, 16, v43
	v_mov_b32_e32 v43, v53
	v_mov_b32_e32 v41, v46
	v_mov_b32_e32 v57, v46
	v_pk_add_f32 v[60:61], v[46:47], v[58:59]
	v_pk_mul_f32 v[46:47], v[46:47], v[58:59]
	v_pk_add_f32 v[44:45], v[40:41], v[44:45] op_sel_hi:[0,1]
	v_mov_b32_e32 v61, v47
	v_pk_add_f32 v[46:47], v[52:53], v[42:43]
	v_pk_mul_f32 v[58:59], v[52:53], v[52:53]
	v_mov_b32_e32 v43, v54
	v_mul_f32_e32 v45, v40, v40
	v_mov_b32_e32 v47, v59
	v_pk_add_f32 v[58:59], v[54:55], v[56:57]
	v_pk_mul_f32 v[40:41], v[54:55], v[40:41]
	v_mov_b32_e32 v53, v56
	v_pk_mul_f32 v[42:43], v[42:43], v[42:43]
	v_mov_b32_e32 v59, v41
	v_pk_fma_f32 v[42:43], v[52:53], v[52:53], v[42:43]
	v_pk_add_f32 v[44:45], v[44:45], v[60:61]
	v_pk_add_f32 v[40:41], v[46:47], v[58:59]
	v_pk_add_f32 v[42:43], v[42:43], v[42:43] op_sel_hi:[0,1]
	v_pk_add_f32 v[40:41], v[44:45], v[40:41]
	v_mov_b32_e32 v137, v43
	v_pk_add_f32 v[44:45], v[40:41], v[136:137]

.LBB0_259:
	s_nop 0
	s_nop 0
	v_permlane32_swap_b32_e32 v183, v184
	v_add_f32_e32 v32, v183, v184
	v_fmamk_f32 v32, v32, 0x3a800000, v177
	v_mov_b64_e32 v[38:39], s[30:31]
	s_waitcnt lgkmcnt(1)
	s_waitcnt lgkmcnt(0)
	v_rsq_f32_e32 v34, v32
	s_nop 0
	v_pk_mul_f32 v[28:29], v[28:29], v[34:35] op_sel_hi:[1,0]
	v_pk_mul_f32 v[30:31], v[30:31], v[34:35] op_sel_hi:[1,0]
	v_and_b32_e32 v37, 0x7fffffff, v29
	v_and_b32_e32 v36, 0x7fffffff, v28
	v_pk_fma_f32 v[36:37], v[36:37], s[26:27], 1.0 op_sel_hi:[1,0,0]
	v_pk_mul_f32 v[42:43], v[28:29], v[28:29]
	v_rcp_f32_e32 v36, v36
	v_rcp_f32_e32 v37, v37
	v_pk_mul_f32 v[42:43], v[42:43], s[40:41] op_sel_hi:[1,0]
	v_and_b32_e32 v45, 0x7fffffff, v31
	v_exp_f32_e32 v42, v42
	v_pk_fma_f32 v[40:41], v[36:37], s[28:29], v[38:39] op_sel_hi:[1,0,0]
	v_exp_f32_e32 v43, v43
	v_pk_fma_f32 v[40:41], v[36:37], v[40:41], s[34:35] op_sel_hi:[1,1,0]
	v_and_b32_e32 v44, 0x7fffffff, v30
	v_pk_fma_f32 v[40:41], v[36:37], v[40:41], s[36:37] op_sel_hi:[1,1,0]
	v_pk_fma_f32 v[44:45], v[44:45], s[26:27], 1.0 op_sel_hi:[1,0,0]
	v_pk_fma_f32 v[40:41], v[36:37], v[40:41], s[38:39] op_sel_hi:[1,1,0]
	v_rcp_f32_e32 v44, v44
	v_pk_mul_f32 v[36:37], v[36:37], v[40:41]
	v_rcp_f32_e32 v45, v45
	v_pk_mul_f32 v[36:37], v[42:43], v[36:37]
	v_cmp_gt_f32_e32 vcc, 0, v28
	v_pk_mul_f32 v[42:43], v[28:29], v[36:37]
	v_pk_fma_f32 v[36:37], v[28:29], v[36:37], v[28:29] neg_lo:[1,0,0] neg_hi:[1,0,0]
	v_pk_mul_f32 v[26:27], v[26:27], v[34:35] op_sel_hi:[1,0]
	v_pk_mul_f32 v[24:25], v[24:25], v[34:35] op_sel_hi:[1,0]
	v_pk_mul_f32 v[40:41], v[30:31], v[30:31]
	v_cndmask_b32_e32 v35, v36, v42, vcc
	v_cmp_gt_f32_e32 vcc, 0, v29
	v_pk_fma_f32 v[28:29], v[44:45], s[28:29], v[38:39] op_sel_hi:[1,0,0]
	v_lshlrev_b64 v[32:33], 12, v[150:151]
	v_cndmask_b32_e32 v42, v37, v43, vcc
	v_pk_mul_f32 v[36:37], v[40:41], s[40:41] op_sel_hi:[1,0]
	v_pk_fma_f32 v[28:29], v[44:45], v[28:29], s[34:35] op_sel_hi:[1,1,0]
	v_exp_f32_e32 v36, v36
	v_exp_f32_e32 v37, v37
	v_pk_fma_f32 v[28:29], v[44:45], v[28:29], s[36:37] op_sel_hi:[1,1,0]
	v_and_b32_e32 v41, 0x7fffffff, v25
	v_and_b32_e32 v40, 0x7fffffff, v24
	v_pk_fma_f32 v[28:29], v[44:45], v[28:29], s[38:39] op_sel_hi:[1,1,0]
	v_pk_fma_f32 v[40:41], v[40:41], s[26:27], 1.0 op_sel_hi:[1,0,0]
	v_pk_mul_f32 v[28:29], v[44:45], v[28:29]
	v_rcp_f32_e32 v40, v40
	v_rcp_f32_e32 v41, v41
	v_pk_mul_f32 v[28:29], v[36:37], v[28:29]
	v_cmp_gt_f32_e32 vcc, 0, v30
	v_pk_mul_f32 v[36:37], v[30:31], v[28:29]
	v_pk_fma_f32 v[28:29], v[30:31], v[28:29], v[30:31] neg_lo:[1,0,0] neg_hi:[1,0,0]
	v_lshl_add_u64 v[32:33], v[152:153], 0, v[32:33]
	v_cndmask_b32_e32 v43, v28, v36, vcc
	v_cmp_gt_f32_e32 vcc, 0, v31
	v_pk_mul_f32 v[30:31], v[24:25], v[24:25]
	s_nop 0
	v_cndmask_b32_e32 v44, v29, v37, vcc
	v_pk_fma_f32 v[28:29], v[40:41], s[28:29], v[38:39] op_sel_hi:[1,0,0]
	v_pk_mul_f32 v[30:31], v[30:31], s[40:41] op_sel_hi:[1,0]
	v_pk_fma_f32 v[28:29], v[40:41], v[28:29], s[34:35] op_sel_hi:[1,1,0]
	v_exp_f32_e32 v30, v30
	v_pk_fma_f32 v[28:29], v[40:41], v[28:29], s[36:37] op_sel_hi:[1,1,0]
	v_exp_f32_e32 v31, v31
	v_pk_fma_f32 v[28:29], v[40:41], v[28:29], s[38:39] op_sel_hi:[1,1,0]
	v_cmp_gt_f32_e32 vcc, 0, v24
	v_pk_mul_f32 v[28:29], v[40:41], v[28:29]
	v_and_b32_e32 v41, 0x7fffffff, v27
	v_and_b32_e32 v40, 0x7fffffff, v26
	v_pk_fma_f32 v[40:41], v[40:41], s[26:27], 1.0 op_sel_hi:[1,0,0]
	v_pk_mul_f32 v[28:29], v[30:31], v[28:29]
	v_rcp_f32_e32 v40, v40
	v_rcp_f32_e32 v41, v41
	v_pk_mul_f32 v[30:31], v[24:25], v[28:29]
	v_pk_fma_f32 v[28:29], v[24:25], v[28:29], v[24:25] neg_lo:[1,0,0] neg_hi:[1,0,0]
	v_pk_mul_f32 v[36:37], v[26:27], v[26:27]
	v_cndmask_b32_e32 v30, v28, v30, vcc
	v_cmp_gt_f32_e32 vcc, 0, v25
	v_pk_fma_f32 v[24:25], v[40:41], s[28:29], v[38:39] op_sel_hi:[1,0,0]
	s_nop 0
	v_cndmask_b32_e32 v31, v29, v31, vcc
	v_pk_mul_f32 v[28:29], v[36:37], s[40:41] op_sel_hi:[1,0]
	v_pk_fma_f32 v[24:25], v[40:41], v[24:25], s[34:35] op_sel_hi:[1,1,0]
	v_exp_f32_e32 v28, v28
	v_exp_f32_e32 v29, v29
	v_pk_fma_f32 v[24:25], v[40:41], v[24:25], s[36:37] op_sel_hi:[1,1,0]
	v_cmp_gt_f32_e32 vcc, 0, v26
	v_pk_fma_f32 v[24:25], v[40:41], v[24:25], s[38:39] op_sel_hi:[1,1,0]
	s_nop 0
	v_pk_mul_f32 v[24:25], v[40:41], v[24:25]
	s_nop 0
	v_pk_mul_f32 v[24:25], v[28:29], v[24:25]
	s_nop 0
	v_pk_mul_f32 v[28:29], v[26:27], v[24:25]
	v_pk_fma_f32 v[24:25], v[26:27], v[24:25], v[26:27] neg_lo:[1,0,0] neg_hi:[1,0,0]
	s_nop 0
	v_cndmask_b32_e32 v28, v24, v28, vcc
	v_cmp_gt_f32_e32 vcc, 0, v27
	v_cvt_pk_bf16_f32 v24, v35, v42
	s_nop 1
	v_cndmask_b32_e32 v27, v25, v29, vcc
	v_cvt_pk_bf16_f32 v25, v43, v44
	v_cvt_pk_bf16_f32 v26, v30, v31
	v_cvt_pk_bf16_f32 v27, v28, v27
	v_mov_b32_e32 v28, 0
	s_and_b64 vcc, exec, s[8:9]
	v_mov_b32_e32 v29, 0
	global_store_dwordx4 v[32:33], v[24:27], off
	s_cbranch_vccnz .LBB0_261
	v_and_b32_e32 v29, 16, v24
	v_and_b32_e32 v28, 0xffff0000, v24
	v_lshlrev_b32_e32 v37, 16, v25
	v_lshlrev_b32_e32 v36, 16, v26
	v_and_b32_e32 v30, 0xffff0000, v25
	v_mov_b32_e32 v31, v28
	v_pk_mov_b32 v[42:43], v[36:37], v[28:29] op_sel:[1,0]
	v_lshlrev_b32_e32 v24, 16, v24
	v_and_b32_e32 v38, 0xffff0000, v27
	v_mov_b32_e32 v39, v30
	v_and_b32_e32 v26, 0xffff0000, v26
	v_lshlrev_b32_e32 v40, 16, v27
	v_mov_b32_e32 v27, v37
	v_mov_b32_e32 v25, v30
	v_mov_b32_e32 v41, v30
	v_pk_add_f32 v[44:45], v[30:31], v[42:43]
	v_pk_mul_f32 v[30:31], v[30:31], v[42:43]
	v_pk_add_f32 v[28:29], v[24:25], v[28:29] op_sel_hi:[0,1]
	v_mov_b32_e32 v45, v31
	v_pk_add_f32 v[30:31], v[36:37], v[26:27]
	v_pk_mul_f32 v[42:43], v[36:37], v[36:37]
	v_mov_b32_e32 v27, v38
	v_mul_f32_e32 v29, v24, v24
	v_mov_b32_e32 v31, v43
	v_pk_add_f32 v[42:43], v[38:39], v[40:41]
	v_pk_mul_f32 v[24:25], v[38:39], v[24:25]
	v_mov_b32_e32 v37, v40
	v_pk_mul_f32 v[26:27], v[26:27], v[26:27]
	v_mov_b32_e32 v43, v25
	v_pk_fma_f32 v[26:27], v[36:37], v[36:37], v[26:27]
	v_pk_add_f32 v[28:29], v[28:29], v[44:45]
	v_pk_add_f32 v[24:25], v[30:31], v[42:43]
	v_pk_add_f32 v[26:27], v[26:27], v[26:27] op_sel_hi:[0,1]
	v_pk_add_f32 v[24:25], v[28:29], v[24:25]
	v_mov_b32_e32 v137, v27
	v_pk_add_f32 v[28:29], v[24:25], v[136:137]

.LBB0_265:
	s_nop 0
	s_nop 0
	v_permlane32_swap_b32_e32 v181, v182
	v_add_f32_e32 v16, v181, v182
	v_fmamk_f32 v16, v16, 0x3a800000, v177
	v_mov_b64_e32 v[22:23], s[30:31]
	s_waitcnt lgkmcnt(1)
	s_waitcnt lgkmcnt(0)
	v_rsq_f32_e32 v18, v16
	s_nop 0
	v_pk_mul_f32 v[12:13], v[12:13], v[18:19] op_sel_hi:[1,0]
	v_pk_mul_f32 v[14:15], v[14:15], v[18:19] op_sel_hi:[1,0]
	v_and_b32_e32 v21, 0x7fffffff, v13
	v_and_b32_e32 v20, 0x7fffffff, v12
	v_pk_fma_f32 v[20:21], v[20:21], s[26:27], 1.0 op_sel_hi:[1,0,0]
	v_pk_mul_f32 v[26:27], v[12:13], v[12:13]
	v_rcp_f32_e32 v20, v20
	v_rcp_f32_e32 v21, v21
	v_pk_mul_f32 v[26:27], v[26:27], s[40:41] op_sel_hi:[1,0]
	v_and_b32_e32 v29, 0x7fffffff, v15
	v_exp_f32_e32 v26, v26
	v_pk_fma_f32 v[24:25], v[20:21], s[28:29], v[22:23] op_sel_hi:[1,0,0]
	v_exp_f32_e32 v27, v27
	v_pk_fma_f32 v[24:25], v[20:21], v[24:25], s[34:35] op_sel_hi:[1,1,0]
	v_and_b32_e32 v28, 0x7fffffff, v14
	v_pk_fma_f32 v[24:25], v[20:21], v[24:25], s[36:37] op_sel_hi:[1,1,0]
	v_pk_fma_f32 v[28:29], v[28:29], s[26:27], 1.0 op_sel_hi:[1,0,0]
	v_pk_fma_f32 v[24:25], v[20:21], v[24:25], s[38:39] op_sel_hi:[1,1,0]
	v_rcp_f32_e32 v28, v28
	v_pk_mul_f32 v[20:21], v[20:21], v[24:25]
	v_rcp_f32_e32 v29, v29
	v_pk_mul_f32 v[20:21], v[26:27], v[20:21]
	v_cmp_gt_f32_e32 vcc, 0, v12
	v_pk_mul_f32 v[26:27], v[12:13], v[20:21]
	v_pk_fma_f32 v[20:21], v[12:13], v[20:21], v[12:13] neg_lo:[1,0,0] neg_hi:[1,0,0]
	v_pk_mul_f32 v[10:11], v[10:11], v[18:19] op_sel_hi:[1,0]
	v_pk_mul_f32 v[8:9], v[8:9], v[18:19] op_sel_hi:[1,0]
	v_pk_mul_f32 v[24:25], v[14:15], v[14:15]
	v_cndmask_b32_e32 v19, v20, v26, vcc
	v_cmp_gt_f32_e32 vcc, 0, v13
	v_pk_fma_f32 v[12:13], v[28:29], s[28:29], v[22:23] op_sel_hi:[1,0,0]
	v_lshlrev_b64 v[16:17], 12, v[148:149]
	v_cndmask_b32_e32 v26, v21, v27, vcc
	v_pk_mul_f32 v[20:21], v[24:25], s[40:41] op_sel_hi:[1,0]
	v_pk_fma_f32 v[12:13], v[28:29], v[12:13], s[34:35] op_sel_hi:[1,1,0]
	v_exp_f32_e32 v20, v20
	v_exp_f32_e32 v21, v21
	v_pk_fma_f32 v[12:13], v[28:29], v[12:13], s[36:37] op_sel_hi:[1,1,0]
	v_and_b32_e32 v25, 0x7fffffff, v9
	v_and_b32_e32 v24, 0x7fffffff, v8
	v_pk_fma_f32 v[12:13], v[28:29], v[12:13], s[38:39] op_sel_hi:[1,1,0]
	v_pk_fma_f32 v[24:25], v[24:25], s[26:27], 1.0 op_sel_hi:[1,0,0]
	v_pk_mul_f32 v[12:13], v[28:29], v[12:13]
	v_rcp_f32_e32 v24, v24
	v_rcp_f32_e32 v25, v25
	v_pk_mul_f32 v[12:13], v[20:21], v[12:13]
	v_cmp_gt_f32_e32 vcc, 0, v14
	v_pk_mul_f32 v[20:21], v[14:15], v[12:13]
	v_pk_fma_f32 v[12:13], v[14:15], v[12:13], v[14:15] neg_lo:[1,0,0] neg_hi:[1,0,0]
	v_lshl_add_u64 v[16:17], v[152:153], 0, v[16:17]
	v_cndmask_b32_e32 v27, v12, v20, vcc
	v_cmp_gt_f32_e32 vcc, 0, v15
	v_pk_mul_f32 v[14:15], v[8:9], v[8:9]
	s_nop 0
	v_cndmask_b32_e32 v28, v13, v21, vcc
	v_pk_fma_f32 v[12:13], v[24:25], s[28:29], v[22:23] op_sel_hi:[1,0,0]
	v_pk_mul_f32 v[14:15], v[14:15], s[40:41] op_sel_hi:[1,0]
	v_pk_fma_f32 v[12:13], v[24:25], v[12:13], s[34:35] op_sel_hi:[1,1,0]
	v_exp_f32_e32 v14, v14
	v_pk_fma_f32 v[12:13], v[24:25], v[12:13], s[36:37] op_sel_hi:[1,1,0]
	v_exp_f32_e32 v15, v15
	v_pk_fma_f32 v[12:13], v[24:25], v[12:13], s[38:39] op_sel_hi:[1,1,0]
	v_cmp_gt_f32_e32 vcc, 0, v8
	v_pk_mul_f32 v[12:13], v[24:25], v[12:13]
	v_and_b32_e32 v25, 0x7fffffff, v11
	v_and_b32_e32 v24, 0x7fffffff, v10
	v_pk_fma_f32 v[24:25], v[24:25], s[26:27], 1.0 op_sel_hi:[1,0,0]
	v_pk_mul_f32 v[12:13], v[14:15], v[12:13]
	v_rcp_f32_e32 v24, v24
	v_rcp_f32_e32 v25, v25
	v_pk_mul_f32 v[14:15], v[8:9], v[12:13]
	v_pk_fma_f32 v[12:13], v[8:9], v[12:13], v[8:9] neg_lo:[1,0,0] neg_hi:[1,0,0]
	v_pk_mul_f32 v[20:21], v[10:11], v[10:11]
	v_cndmask_b32_e32 v14, v12, v14, vcc
	v_cmp_gt_f32_e32 vcc, 0, v9
	v_pk_fma_f32 v[8:9], v[24:25], s[28:29], v[22:23] op_sel_hi:[1,0,0]
	s_nop 0
	v_cndmask_b32_e32 v15, v13, v15, vcc
	v_pk_mul_f32 v[12:13], v[20:21], s[40:41] op_sel_hi:[1,0]
	v_pk_fma_f32 v[8:9], v[24:25], v[8:9], s[34:35] op_sel_hi:[1,1,0]
	v_exp_f32_e32 v12, v12
	v_exp_f32_e32 v13, v13
	v_pk_fma_f32 v[8:9], v[24:25], v[8:9], s[36:37] op_sel_hi:[1,1,0]
	v_cmp_gt_f32_e32 vcc, 0, v10
	v_pk_fma_f32 v[8:9], v[24:25], v[8:9], s[38:39] op_sel_hi:[1,1,0]
	s_nop 0
	v_pk_mul_f32 v[8:9], v[24:25], v[8:9]
	s_nop 0
	v_pk_mul_f32 v[8:9], v[12:13], v[8:9]
	s_nop 0
	v_pk_mul_f32 v[12:13], v[10:11], v[8:9]
	v_pk_fma_f32 v[8:9], v[10:11], v[8:9], v[10:11] neg_lo:[1,0,0] neg_hi:[1,0,0]
	s_nop 0
	v_cndmask_b32_e32 v12, v8, v12, vcc
	v_cmp_gt_f32_e32 vcc, 0, v11
	v_cvt_pk_bf16_f32 v8, v19, v26
	s_nop 1
	v_cndmask_b32_e32 v11, v9, v13, vcc
	v_cvt_pk_bf16_f32 v9, v27, v28
	v_cvt_pk_bf16_f32 v10, v14, v15
	v_cvt_pk_bf16_f32 v11, v12, v11
	v_mov_b32_e32 v12, 0
	s_and_b64 vcc, exec, s[8:9]
	v_mov_b32_e32 v13, 0
	global_store_dwordx4 v[16:17], v[8:11], off
	s_cbranch_vccnz .LBB0_267
	v_and_b32_e32 v13, 16, v8
	v_and_b32_e32 v12, 0xffff0000, v8
	v_lshlrev_b32_e32 v21, 16, v9
	v_lshlrev_b32_e32 v20, 16, v10
	v_and_b32_e32 v14, 0xffff0000, v9
	v_mov_b32_e32 v15, v12
	v_pk_mov_b32 v[26:27], v[20:21], v[12:13] op_sel:[1,0]
	v_lshlrev_b32_e32 v8, 16, v8
	v_and_b32_e32 v22, 0xffff0000, v11
	v_mov_b32_e32 v23, v14
	v_and_b32_e32 v10, 0xffff0000, v10
	v_lshlrev_b32_e32 v24, 16, v11
	v_mov_b32_e32 v11, v21
	v_mov_b32_e32 v9, v14
	v_mov_b32_e32 v25, v14
	v_pk_add_f32 v[28:29], v[14:15], v[26:27]
	v_pk_mul_f32 v[14:15], v[14:15], v[26:27]
	v_pk_add_f32 v[12:13], v[8:9], v[12:13] op_sel_hi:[0,1]
	v_mov_b32_e32 v29, v15
	v_pk_add_f32 v[14:15], v[20:21], v[10:11]
	v_pk_mul_f32 v[26:27], v[20:21], v[20:21]
	v_mov_b32_e32 v11, v22
	v_mul_f32_e32 v13, v8, v8
	v_mov_b32_e32 v15, v27
	v_pk_add_f32 v[26:27], v[22:23], v[24:25]
	v_pk_mul_f32 v[8:9], v[22:23], v[8:9]
	v_mov_b32_e32 v21, v24
	v_pk_mul_f32 v[10:11], v[10:11], v[10:11]
	v_mov_b32_e32 v27, v9
	v_pk_fma_f32 v[10:11], v[20:21], v[20:21], v[10:11]
	v_pk_add_f32 v[12:13], v[12:13], v[28:29]
	v_pk_add_f32 v[8:9], v[14:15], v[26:27]
	v_pk_add_f32 v[10:11], v[10:11], v[10:11] op_sel_hi:[0,1]
	v_pk_add_f32 v[8:9], v[12:13], v[8:9]
	v_mov_b32_e32 v137, v11
	v_pk_add_f32 v[12:13], v[8:9], v[136:137]

.LBB0_486:
	v_lshl_add_u32 v162, s8, 8, v159
	s_cmp_eq_u32 s8, s62
	s_cbranch_scc1 .Lrstd_reuse_p4
	s_mov_b64 s[60:61], 0x2000
	v_lshlrev_b32_e32 v204, 6, v162
	v_mov_b32_e32 v205, 0
	v_mbcnt_lo_u32_b32 v248, -1, 0
	v_mbcnt_hi_u32_b32 v248, -1, v248
	v_xor_b32_e32 v248, 16, v248
	v_lshl_add_u64 v[204:205], v[136:137], 0, v[204:205]
	v_lshlrev_b32_e32 v248, 2, v248
	v_lshl_add_u64 v[206:207], v[204:205], 0, s[60:61]
	global_load_dwordx4 v[208:211], v[204:205], off
	global_load_dwordx4 v[212:215], v[204:205], off offset:1024
	global_load_dwordx4 v[216:219], v[204:205], off offset:2048
	global_load_dwordx4 v[220:223], v[204:205], off offset:3072
	global_load_dwordx4 v[224:227], v[206:207], off
	global_load_dwordx4 v[228:231], v[206:207], off offset:1024
	global_load_dwordx4 v[232:235], v[206:207], off offset:2048
	global_load_dwordx4 v[236:239], v[206:207], off offset:3072
	s_waitcnt vmcnt(0)
	v_add_f32_e32 v208, v208, v209
	v_add_f32_e32 v210, v210, v211
	v_add_f32_e32 v212, v212, v213
	v_add_f32_e32 v214, v214, v215
	v_add_f32_e32 v216, v216, v217
	v_add_f32_e32 v218, v218, v219
	v_add_f32_e32 v220, v220, v221
	v_add_f32_e32 v222, v222, v223
	v_add_f32_e32 v224, v224, v225
	v_add_f32_e32 v226, v226, v227
	v_add_f32_e32 v228, v228, v229
	v_add_f32_e32 v230, v230, v231
	v_add_f32_e32 v232, v232, v233
	v_add_f32_e32 v234, v234, v235
	v_add_f32_e32 v236, v236, v237
	v_add_f32_e32 v238, v238, v239
	v_add_f32_e32 v208, v208, v210
	v_add_f32_e32 v212, v212, v214
	v_add_f32_e32 v216, v216, v218
	v_add_f32_e32 v220, v220, v222
	v_add_f32_e32 v224, v224, v226
	v_add_f32_e32 v228, v228, v230
	v_add_f32_e32 v232, v232, v234
	v_add_f32_e32 v236, v236, v238
	v_mov_b32_e32 v209, v208
	v_mov_b32_e32 v213, v212
	v_mov_b32_e32 v217, v216
	v_mov_b32_e32 v221, v220
	v_mov_b32_e32 v225, v224
	v_mov_b32_e32 v229, v228
	v_mov_b32_e32 v233, v232
	v_mov_b32_e32 v237, v236
	s_waitcnt lgkmcnt(0)
	v_permlane16_swap_b32_e32 v208, v209
	v_add_f32_e32 v208, v208, v209
	v_permlane16_swap_b32_e32 v212, v213
	v_add_f32_e32 v212, v212, v213
	v_permlane16_swap_b32_e32 v216, v217
	v_add_f32_e32 v216, v216, v217
	v_permlane16_swap_b32_e32 v220, v221
	v_add_f32_e32 v220, v220, v221
	v_permlane16_swap_b32_e32 v224, v225
	v_add_f32_e32 v224, v224, v225
	v_permlane16_swap_b32_e32 v228, v229
	v_add_f32_e32 v228, v228, v229
	v_permlane16_swap_b32_e32 v232, v233
	v_add_f32_e32 v232, v232, v233
	v_permlane16_swap_b32_e32 v236, v237
	v_add_f32_e32 v236, v236, v237
	v_mov_b32_e32 v209, v208
	v_mov_b32_e32 v213, v212
	v_mov_b32_e32 v217, v216
	v_mov_b32_e32 v221, v220
	v_mov_b32_e32 v225, v224
	v_mov_b32_e32 v229, v228
	v_mov_b32_e32 v233, v232
	v_mov_b32_e32 v237, v236
	s_nop 1
	v_permlane32_swap_b32_e32 v208, v209
	v_permlane32_swap_b32_e32 v212, v213
	v_permlane32_swap_b32_e32 v216, v217
	v_permlane32_swap_b32_e32 v220, v221
	v_permlane32_swap_b32_e32 v224, v225
	v_permlane32_swap_b32_e32 v228, v229
	v_permlane32_swap_b32_e32 v232, v233
	v_permlane32_swap_b32_e32 v236, v237
	v_add_f32_e32 v208, v208, v209
	v_add_f32_e32 v212, v212, v213
	v_add_f32_e32 v216, v216, v217
	v_add_f32_e32 v220, v220, v221
	v_add_f32_e32 v224, v224, v225
	v_add_f32_e32 v228, v228, v229
	v_add_f32_e32 v232, v232, v233
	v_add_f32_e32 v236, v236, v237
	v_fmamk_f32 v208, v208, 0x3a800000, v177
	v_fmamk_f32 v212, v212, 0x3a800000, v177
	v_fmamk_f32 v216, v216, 0x3a800000, v177
	v_fmamk_f32 v220, v220, 0x3a800000, v177
	v_fmamk_f32 v224, v224, 0x3a800000, v177
	v_fmamk_f32 v228, v228, 0x3a800000, v177
	v_fmamk_f32 v232, v232, 0x3a800000, v177
	v_fmamk_f32 v236, v236, 0x3a800000, v177
	v_rsq_f32_e32 v176, v208
	v_rsq_f32_e32 v174, v212
	v_rsq_f32_e32 v172, v216
	v_rsq_f32_e32 v170, v220
	v_rsq_f32_e32 v168, v224
	v_rsq_f32_e32 v166, v228
	v_rsq_f32_e32 v164, v232
	v_rsq_f32_e32 v158, v236
	s_nop 0
	v_mov_b32_e32 v240, v176
	v_mov_b32_e32 v241, v174
	v_mov_b32_e32 v242, v172
	v_mov_b32_e32 v243, v170
	v_mov_b32_e32 v244, v168
	v_mov_b32_e32 v245, v166
	v_mov_b32_e32 v246, v164
	v_mov_b32_e32 v247, v158
	s_mov_b32 s62, s8
	s_branch .Lrstd_done_p4

.LBB0_646:
	v_lshl_add_u32 v170, s12, 8, v188
	v_mov_b32_e32 v196, v170
	v_or_b32_e32 v168, 16, v170
	v_or_b32_e32 v166, 32, v170
	v_or_b32_e32 v164, 48, v170
	v_ashrrev_i32_e32 v171, 31, v170
	v_ashrrev_i32_e32 v169, 31, v168
	v_ashrrev_i32_e32 v167, 31, v166
	v_ashrrev_i32_e32 v165, 31, v164
	v_lshlrev_b64 v[128:129], 6, v[170:171]
	v_lshlrev_b64 v[130:131], 6, v[168:169]
	v_lshlrev_b64 v[156:157], 6, v[166:167]
	v_lshlrev_b64 v[158:159], 6, v[164:165]
	v_add_u32_e32 v162, 0x80, v170
	v_add_u32_e32 v160, 0x90, v170
	v_lshl_add_u64 v[128:129], v[146:147], 0, v[128:129]
	v_lshl_add_u64 v[132:133], v[146:147], 0, v[130:131]
	v_lshl_add_u64 v[156:157], v[146:147], 0, v[156:157]
	v_lshl_add_u64 v[158:159], v[146:147], 0, v[158:159]
	v_ashrrev_i32_e32 v163, 31, v162
	v_ashrrev_i32_e32 v161, 31, v160
	global_load_dwordx4 v[128:131], v[128:129], off
	s_nop 0
	global_load_dwordx4 v[132:135], v[132:133], off
	s_nop 0
	global_load_dwordx4 v[172:175], v[156:157], off
	global_load_dwordx4 v[176:179], v[158:159], off
	v_lshlrev_b64 v[156:157], 6, v[162:163]
	v_lshlrev_b64 v[158:159], 6, v[160:161]
	v_lshl_add_u64 v[156:157], v[146:147], 0, v[156:157]
	v_lshl_add_u64 v[158:159], v[146:147], 0, v[158:159]
	global_load_dwordx4 v[180:183], v[156:157], off
	global_load_dwordx4 v[184:187], v[158:159], off
	v_add_u32_e32 v158, 0xa0, v170
	v_ashrrev_i32_e32 v159, 31, v158
	v_lshlrev_b64 v[156:157], 6, v[158:159]
	v_lshl_add_u64 v[156:157], v[146:147], 0, v[156:157]
	global_load_dwordx4 v[204:207], v[156:157], off
	v_add_u32_e32 v156, 0xb0, v170
	v_ashrrev_i32_e32 v157, 31, v156
	v_lshlrev_b64 v[198:199], 6, v[156:157]
	v_lshl_add_u64 v[198:199], v[146:147], 0, v[198:199]
	global_load_dwordx4 v[208:211], v[198:199], off
	v_and_b32_e32 v198, 64, v194
	v_xor_b32_e32 v144, 16, v194
	v_add_u32_e32 v198, 64, v198
	v_cmp_lt_i32_e32 vcc, v144, v198
	v_xor_b32_e32 v199, 32, v194
	s_ashr_i32 s4, s16, 2
	v_cndmask_b32_e32 v144, v194, v144, vcc
	v_cmp_lt_i32_e32 vcc, v199, v198
	v_lshlrev_b32_e32 v198, 2, v144
	s_cmp_lg_u32 s4, 1
	v_cndmask_b32_e32 v199, v194, v199, vcc
	v_lshlrev_b32_e32 v200, 2, v199
	s_cselect_b64 s[12:13], -1, 0
	s_and_b64 s[22:23], s[36:37], s[12:13]
	s_and_b64 s[46:47], s[22:23], s[6:7]
	v_mov_b32_e32 v226, 1.0
	v_mov_b32_e32 v227, 1.0
	v_mov_b32_e32 v228, 1.0
	v_mov_b32_e32 v229, 1.0
	v_mov_b32_e32 v230, 1.0
	v_mov_b32_e32 v231, 1.0
	v_mov_b32_e32 v232, 1.0
	v_mov_b32_e32 v233, 1.0
	s_and_saveexec_b64 s[32:33], s[46:47]
	v_lshlrev_b32_e32 v250, 6, v196
	v_and_b32_e32 v250, 0x7ffc0, v250
	global_load_dwordx4 v[218:221], v250, s[28:29] offset:32
	global_load_dwordx4 v[222:225], v250, s[28:29] offset:48
	global_load_dwordx4 v[226:229], v250, s[28:29]
	global_load_dwordx4 v[230:233], v250, s[28:29] offset:16
	s_mov_b64 exec, s[32:33]
	s_waitcnt vmcnt(4)
	v_add_f32_e32 v128, v128, v129
	v_add_f32_e32 v129, v130, v131
	v_add_f32_e32 v128, v128, v129
	v_add_f32_e32 v129, v132, v133
	v_add_f32_e32 v130, v134, v135
	v_add_f32_e32 v131, v172, v173
	v_add_f32_e32 v132, v174, v175
	v_add_f32_e32 v133, v176, v177
	v_add_f32_e32 v134, v178, v179
	v_add_f32_e32 v135, v180, v181
	v_add_f32_e32 v144, v182, v183
	v_add_f32_e32 v172, v184, v185
	v_add_f32_e32 v173, v186, v187
	v_add_f32_e32 v174, v204, v205
	v_add_f32_e32 v175, v206, v207
	v_add_f32_e32 v129, v129, v130
	v_add_f32_e32 v130, v131, v132
	v_add_f32_e32 v176, v208, v209
	v_add_f32_e32 v177, v210, v211
	v_add_f32_e32 v131, v133, v134
	v_add_f32_e32 v132, v135, v144
	v_add_f32_e32 v133, v172, v173
	v_add_f32_e32 v134, v174, v175
	v_add_f32_e32 v135, v176, v177
	v_mov_b32_e32 v178, v128
	v_mov_b32_e32 v172, v129
	v_mov_b32_e32 v173, v130
	v_mov_b32_e32 v174, v131
	v_mov_b32_e32 v175, v132
	v_mov_b32_e32 v176, v133
	v_mov_b32_e32 v177, v134
	v_mov_b32_e32 v179, v135
	s_waitcnt lgkmcnt(7)
	v_permlane16_swap_b32_e32 v128, v178
	v_add_f32_e32 v144, v128, v178
	s_waitcnt lgkmcnt(6)
	v_permlane16_swap_b32_e32 v129, v172
	v_add_f32_e32 v213, v129, v172
	s_waitcnt lgkmcnt(5)
	v_permlane16_swap_b32_e32 v130, v173
	v_add_f32_e32 v211, v130, v173
	s_waitcnt lgkmcnt(4)
	v_permlane16_swap_b32_e32 v131, v174
	v_add_f32_e32 v209, v131, v174
	s_waitcnt lgkmcnt(3)
	v_permlane16_swap_b32_e32 v132, v175
	v_add_f32_e32 v207, v132, v175
	s_waitcnt lgkmcnt(2)
	v_permlane16_swap_b32_e32 v133, v176
	v_add_f32_e32 v205, v133, v176
	s_waitcnt lgkmcnt(1)
	v_permlane16_swap_b32_e32 v134, v177
	v_add_f32_e32 v201, v134, v177
	s_waitcnt lgkmcnt(0)
	v_permlane16_swap_b32_e32 v135, v179
	v_add_f32_e32 v199, v135, v179
	v_mov_b32_e32 v180, v144
	v_mov_b32_e32 v214, v213
	v_mov_b32_e32 v212, v211
	v_mov_b32_e32 v210, v209
	v_mov_b32_e32 v208, v207
	v_mov_b32_e32 v206, v205
	v_mov_b32_e32 v204, v201
	v_mov_b32_e32 v200, v199
	v_mov_b32_e32 v176, 0
	v_mov_b32_e32 v177, 0
	v_mov_b32_e32 v178, 0
	v_mov_b32_e32 v179, 0
	v_mov_b32_e32 v174, 0
	v_mov_b32_e32 v175, 0
	v_mov_b32_e32 v172, 0
	v_mov_b32_e32 v173, 0
	v_mov_b32_e32 v242, 1.0
	v_mov_b32_e32 v243, 1.0
	v_mov_b32_e32 v244, 1.0
	v_mov_b32_e32 v245, 1.0
	v_mov_b32_e32 v246, 1.0
	v_mov_b32_e32 v247, 1.0
	v_mov_b32_e32 v248, 1.0
	v_mov_b32_e32 v249, 1.0
	s_and_saveexec_b64 s[12:13], s[46:47]
	s_cbranch_execz .LBB0_648
	v_add_u32_e32 v250, 0x10, v196
	v_lshlrev_b32_e32 v250, 6, v250
	v_and_b32_e32 v250, 0x7ffc0, v250
	global_load_dwordx4 v[234:237], v250, s[28:29] offset:32
	global_load_dwordx4 v[238:241], v250, s[28:29] offset:48
	global_load_dwordx4 v[242:245], v250, s[28:29]
	global_load_dwordx4 v[246:249], v250, s[28:29] offset:16
	s_waitcnt vmcnt(7)
	v_xor_b32_e32 v179, 0x80000000, v221
	v_xor_b32_e32 v178, 0x80000000, v220
	v_xor_b32_e32 v177, 0x80000000, v219
	v_xor_b32_e32 v176, 0x80000000, v218
	s_waitcnt vmcnt(6)
	v_xor_b32_e32 v181, 0x80000000, v225
	v_xor_b32_e32 v186, 0x80000000, v224
	v_xor_b32_e32 v187, 0x80000000, v223
	v_xor_b32_e32 v215, 0x80000000, v222
	v_cndmask_b32_e64 v176, v218, v176, s[8:9]
	v_cndmask_b32_e64 v177, v219, v177, s[8:9]
	v_cndmask_b32_e64 v178, v220, v178, s[8:9]
	v_cndmask_b32_e64 v179, v221, v179, s[8:9]
	v_cndmask_b32_e64 v174, v222, v215, s[8:9]
	v_cndmask_b32_e64 v175, v223, v187, s[8:9]
	v_cndmask_b32_e64 v172, v224, v186, s[8:9]
	v_cndmask_b32_e64 v173, v225, v181, s[8:9]
.LBB0_648:
	s_or_b64 exec, exec, s[12:13]
	s_waitcnt lgkmcnt(7)
	s_nop 0
	v_permlane32_swap_b32_e32 v144, v180
	v_add_f32_e32 v144, v144, v180
	v_fmamk_f32 v144, v144, 0x3a800000, v195
	v_rsq_f32_e32 v180, v144
	s_nop 0
	v_pk_mul_f32 v[184:185], v[122:123], v[180:181] op_sel_hi:[1,0]
	v_cndmask_b32_e64 v122, 0, 1, s[22:23]
	v_pk_mul_f32 v[126:127], v[126:127], v[180:181] op_sel_hi:[1,0]
	v_pk_mul_f32 v[182:183], v[124:125], v[180:181] op_sel_hi:[1,0]
	v_cmp_ne_u32_e64 s[12:13], 1, v122
	s_andn2_b64 vcc, exec, s[22:23]
	v_pk_mul_f32 v[186:187], v[120:121], v[180:181] op_sel_hi:[1,0]
	s_cbranch_vccnz .LBB0_650
	ds_bpermute_b32 v120, v198, v182
	ds_bpermute_b32 v121, v198, v183
	ds_bpermute_b32 v122, v198, v186
	ds_bpermute_b32 v124, v198, v126
	ds_bpermute_b32 v125, v198, v127
	ds_bpermute_b32 v123, v198, v187
	ds_bpermute_b32 v216, v198, v184
	ds_bpermute_b32 v217, v198, v185
	s_waitcnt lgkmcnt(6)
	v_pk_mul_f32 v[120:121], v[176:177], v[120:121]
	s_waitcnt lgkmcnt(3)
	v_pk_mul_f32 v[124:125], v[178:179], v[124:125]
	s_waitcnt vmcnt(5)
	v_pk_fma_f32 v[182:183], v[182:183], v[226:227], v[120:121]
	s_waitcnt lgkmcnt(2)
	v_pk_mul_f32 v[120:121], v[174:175], v[122:123]
	s_waitcnt lgkmcnt(0)
	v_pk_mul_f32 v[122:123], v[172:173], v[216:217]
	v_pk_fma_f32 v[126:127], v[126:127], v[228:229], v[124:125]
	s_waitcnt vmcnt(4)
	v_pk_fma_f32 v[184:185], v[184:185], v[232:233], v[122:123]
	v_pk_fma_f32 v[186:187], v[186:187], v[230:231], v[120:121]

.LBB0_654:
	s_or_b64 exec, exec, s[4:5]
	s_waitcnt lgkmcnt(6)
	s_nop 0
	v_permlane32_swap_b32_e32 v213, v214
	v_add_f32_e32 v132, v213, v214
	v_fmamk_f32 v132, v132, 0x3a800000, v195
	v_rsq_f32_e32 v132, v132
	s_nop 0
	v_pk_mul_f32 v[110:111], v[110:111], v[132:133] op_sel_hi:[1,0]
	v_pk_mul_f32 v[108:109], v[108:109], v[132:133] op_sel_hi:[1,0]
	v_pk_mul_f32 v[134:135], v[106:107], v[132:133] op_sel_hi:[1,0]
	s_and_b64 vcc, exec, s[12:13]
	v_pk_mul_f32 v[170:171], v[104:105], v[132:133] op_sel_hi:[1,0]
	s_cbranch_vccnz .LBB0_656
	ds_bpermute_b32 v104, v198, v108
	ds_bpermute_b32 v105, v198, v109
	ds_bpermute_b32 v106, v198, v170
	ds_bpermute_b32 v172, v198, v110
	ds_bpermute_b32 v173, v198, v111
	ds_bpermute_b32 v107, v198, v171
	ds_bpermute_b32 v174, v198, v134
	ds_bpermute_b32 v175, v198, v135
	s_waitcnt lgkmcnt(6)
	v_pk_mul_f32 v[104:105], v[128:129], v[104:105]
	s_waitcnt lgkmcnt(3)
	v_pk_mul_f32 v[172:173], v[130:131], v[172:173]
	s_waitcnt vmcnt(5)
	v_pk_fma_f32 v[108:109], v[108:109], v[242:243], v[104:105]
	s_waitcnt lgkmcnt(2)
	v_pk_mul_f32 v[104:105], v[126:127], v[106:107]
	s_waitcnt lgkmcnt(0)
	v_pk_mul_f32 v[106:107], v[124:125], v[174:175]
	v_pk_fma_f32 v[110:111], v[110:111], v[244:245], v[172:173]
	s_waitcnt vmcnt(4)
	v_pk_fma_f32 v[134:135], v[134:135], v[248:249], v[106:107]
	v_pk_fma_f32 v[170:171], v[170:171], v[246:247], v[104:105]

.LBB0_660:
	s_or_b64 exec, exec, s[4:5]
	s_waitcnt vmcnt(6) lgkmcnt(5)
	s_nop 0
	v_permlane32_swap_b32_e32 v211, v212
	v_add_f32_e32 v112, v211, v212
	v_fmamk_f32 v112, v112, 0x3a800000, v195
	v_rsq_f32_e32 v112, v112
	s_nop 0
	v_pk_mul_f32 v[94:95], v[94:95], v[112:113] op_sel_hi:[1,0]
	v_pk_mul_f32 v[92:93], v[92:93], v[112:113] op_sel_hi:[1,0]
	v_pk_mul_f32 v[114:115], v[90:91], v[112:113] op_sel_hi:[1,0]
	s_and_b64 vcc, exec, s[12:13]
	v_pk_mul_f32 v[116:117], v[88:89], v[112:113] op_sel_hi:[1,0]
	s_cbranch_vccnz .LBB0_662
	ds_bpermute_b32 v88, v198, v92
	ds_bpermute_b32 v89, v198, v93
	ds_bpermute_b32 v90, v198, v116
	ds_bpermute_b32 v118, v198, v94
	ds_bpermute_b32 v119, v198, v95
	ds_bpermute_b32 v91, v198, v117
	ds_bpermute_b32 v124, v198, v114
	ds_bpermute_b32 v125, v198, v115
	s_waitcnt lgkmcnt(6)
	v_pk_mul_f32 v[88:89], v[108:109], v[88:89]
	s_waitcnt lgkmcnt(3)
	v_pk_mul_f32 v[118:119], v[110:111], v[118:119]
	s_waitcnt vmcnt(5)
	v_pk_fma_f32 v[92:93], v[92:93], v[226:227], v[88:89]
	s_waitcnt lgkmcnt(2)
	v_pk_mul_f32 v[88:89], v[106:107], v[90:91]
	s_waitcnt lgkmcnt(0)
	v_pk_mul_f32 v[90:91], v[104:105], v[124:125]
	v_pk_fma_f32 v[94:95], v[94:95], v[228:229], v[118:119]
	s_waitcnt vmcnt(4)
	v_pk_fma_f32 v[114:115], v[114:115], v[232:233], v[90:91]
	v_pk_fma_f32 v[116:117], v[116:117], v[230:231], v[88:89]

.LBB0_666:
	s_or_b64 exec, exec, s[4:5]
	s_waitcnt vmcnt(6) lgkmcnt(4)
	s_nop 0
	v_permlane32_swap_b32_e32 v209, v210
	v_add_f32_e32 v96, v209, v210
	v_fmamk_f32 v96, v96, 0x3a800000, v195
	v_rsq_f32_e32 v96, v96
	s_nop 0
	v_pk_mul_f32 v[78:79], v[78:79], v[96:97] op_sel_hi:[1,0]
	v_pk_mul_f32 v[76:77], v[76:77], v[96:97] op_sel_hi:[1,0]
	v_pk_mul_f32 v[98:99], v[74:75], v[96:97] op_sel_hi:[1,0]
	s_and_b64 vcc, exec, s[12:13]
	v_pk_mul_f32 v[100:101], v[72:73], v[96:97] op_sel_hi:[1,0]
	s_cbranch_vccnz .LBB0_668
	ds_bpermute_b32 v72, v198, v76
	ds_bpermute_b32 v73, v198, v77
	ds_bpermute_b32 v74, v198, v100
	ds_bpermute_b32 v102, v198, v78
	ds_bpermute_b32 v103, v198, v79
	ds_bpermute_b32 v75, v198, v101
	ds_bpermute_b32 v104, v198, v98
	ds_bpermute_b32 v105, v198, v99
	s_waitcnt lgkmcnt(6)
	v_pk_mul_f32 v[72:73], v[92:93], v[72:73]
	s_waitcnt lgkmcnt(3)
	v_pk_mul_f32 v[102:103], v[94:95], v[102:103]
	s_waitcnt vmcnt(5)
	v_pk_fma_f32 v[76:77], v[76:77], v[242:243], v[72:73]
	s_waitcnt lgkmcnt(2)
	v_pk_mul_f32 v[72:73], v[90:91], v[74:75]
	s_waitcnt lgkmcnt(0)
	v_pk_mul_f32 v[74:75], v[88:89], v[104:105]
	v_pk_fma_f32 v[78:79], v[78:79], v[244:245], v[102:103]
	s_waitcnt vmcnt(4)
	v_pk_fma_f32 v[98:99], v[98:99], v[248:249], v[74:75]
	v_pk_fma_f32 v[100:101], v[100:101], v[246:247], v[72:73]

.LBB0_672:
	s_or_b64 exec, exec, s[4:5]
	s_waitcnt vmcnt(6) lgkmcnt(3)
	s_nop 0
	v_permlane32_swap_b32_e32 v207, v208
	v_add_f32_e32 v80, v207, v208
	v_fmamk_f32 v80, v80, 0x3a800000, v195
	v_rsq_f32_e32 v80, v80
	s_nop 0
	v_pk_mul_f32 v[62:63], v[62:63], v[80:81] op_sel_hi:[1,0]
	v_pk_mul_f32 v[60:61], v[60:61], v[80:81] op_sel_hi:[1,0]
	v_pk_mul_f32 v[82:83], v[58:59], v[80:81] op_sel_hi:[1,0]
	s_and_b64 vcc, exec, s[12:13]
	v_pk_mul_f32 v[84:85], v[56:57], v[80:81] op_sel_hi:[1,0]
	s_cbranch_vccnz .LBB0_674
	ds_bpermute_b32 v56, v198, v60
	ds_bpermute_b32 v57, v198, v61
	ds_bpermute_b32 v58, v198, v84
	ds_bpermute_b32 v86, v198, v62
	ds_bpermute_b32 v87, v198, v63
	ds_bpermute_b32 v59, v198, v85
	ds_bpermute_b32 v88, v198, v82
	ds_bpermute_b32 v89, v198, v83
	s_waitcnt lgkmcnt(6)
	v_pk_mul_f32 v[56:57], v[76:77], v[56:57]
	s_waitcnt lgkmcnt(3)
	v_pk_mul_f32 v[86:87], v[78:79], v[86:87]
	s_waitcnt vmcnt(5)
	v_pk_fma_f32 v[60:61], v[60:61], v[226:227], v[56:57]
	s_waitcnt lgkmcnt(2)
	v_pk_mul_f32 v[56:57], v[74:75], v[58:59]
	s_waitcnt lgkmcnt(0)
	v_pk_mul_f32 v[58:59], v[72:73], v[88:89]
	v_pk_fma_f32 v[62:63], v[62:63], v[228:229], v[86:87]
	s_waitcnt vmcnt(4)
	v_pk_fma_f32 v[82:83], v[82:83], v[232:233], v[58:59]
	v_pk_fma_f32 v[84:85], v[84:85], v[230:231], v[56:57]

.LBB0_678:
	s_or_b64 exec, exec, s[4:5]
	s_waitcnt vmcnt(6) lgkmcnt(2)
	s_nop 0
	v_permlane32_swap_b32_e32 v205, v206
	v_add_f32_e32 v64, v205, v206
	v_fmamk_f32 v64, v64, 0x3a800000, v195
	v_rsq_f32_e32 v64, v64
	s_nop 0
	v_pk_mul_f32 v[46:47], v[46:47], v[64:65] op_sel_hi:[1,0]
	v_pk_mul_f32 v[44:45], v[44:45], v[64:65] op_sel_hi:[1,0]
	v_pk_mul_f32 v[66:67], v[42:43], v[64:65] op_sel_hi:[1,0]
	s_and_b64 vcc, exec, s[12:13]
	v_pk_mul_f32 v[68:69], v[40:41], v[64:65] op_sel_hi:[1,0]
	s_cbranch_vccnz .LBB0_680
	ds_bpermute_b32 v40, v198, v44
	ds_bpermute_b32 v41, v198, v45
	ds_bpermute_b32 v42, v198, v68
	ds_bpermute_b32 v70, v198, v46
	ds_bpermute_b32 v71, v198, v47
	ds_bpermute_b32 v43, v198, v69
	ds_bpermute_b32 v72, v198, v66
	ds_bpermute_b32 v73, v198, v67
	s_waitcnt lgkmcnt(6)
	v_pk_mul_f32 v[40:41], v[60:61], v[40:41]
	s_waitcnt lgkmcnt(3)
	v_pk_mul_f32 v[70:71], v[62:63], v[70:71]
	s_waitcnt vmcnt(5)
	v_pk_fma_f32 v[44:45], v[44:45], v[242:243], v[40:41]
	s_waitcnt lgkmcnt(2)
	v_pk_mul_f32 v[40:41], v[58:59], v[42:43]
	s_waitcnt lgkmcnt(0)
	v_pk_mul_f32 v[42:43], v[56:57], v[72:73]
	v_pk_fma_f32 v[46:47], v[46:47], v[244:245], v[70:71]
	s_waitcnt vmcnt(4)
	v_pk_fma_f32 v[66:67], v[66:67], v[248:249], v[42:43]
	v_pk_fma_f32 v[68:69], v[68:69], v[246:247], v[40:41]

.LBB0_684:
	s_or_b64 exec, exec, s[4:5]
	s_waitcnt vmcnt(6) lgkmcnt(1)
	s_nop 0
	v_permlane32_swap_b32_e32 v201, v204
	v_add_f32_e32 v48, v201, v204
	v_fmamk_f32 v48, v48, 0x3a800000, v195
	v_rsq_f32_e32 v48, v48
	s_nop 0
	v_pk_mul_f32 v[30:31], v[30:31], v[48:49] op_sel_hi:[1,0]
	v_pk_mul_f32 v[28:29], v[28:29], v[48:49] op_sel_hi:[1,0]
	v_pk_mul_f32 v[50:51], v[26:27], v[48:49] op_sel_hi:[1,0]
	s_and_b64 vcc, exec, s[12:13]
	v_pk_mul_f32 v[52:53], v[24:25], v[48:49] op_sel_hi:[1,0]
	s_cbranch_vccnz .LBB0_686
	ds_bpermute_b32 v24, v198, v28
	ds_bpermute_b32 v25, v198, v29
	ds_bpermute_b32 v26, v198, v52
	ds_bpermute_b32 v54, v198, v30
	ds_bpermute_b32 v55, v198, v31
	ds_bpermute_b32 v27, v198, v53
	ds_bpermute_b32 v56, v198, v50
	ds_bpermute_b32 v57, v198, v51
	s_waitcnt lgkmcnt(6)
	v_pk_mul_f32 v[24:25], v[44:45], v[24:25]
	s_waitcnt lgkmcnt(3)
	v_pk_mul_f32 v[54:55], v[46:47], v[54:55]
	s_waitcnt vmcnt(5)
	v_pk_fma_f32 v[28:29], v[28:29], v[226:227], v[24:25]
	s_waitcnt lgkmcnt(2)
	v_pk_mul_f32 v[24:25], v[42:43], v[26:27]
	s_waitcnt lgkmcnt(0)
	v_pk_mul_f32 v[26:27], v[40:41], v[56:57]
	v_pk_fma_f32 v[30:31], v[30:31], v[228:229], v[54:55]
	s_waitcnt vmcnt(4)
	v_pk_fma_f32 v[50:51], v[50:51], v[232:233], v[26:27]
	v_pk_fma_f32 v[52:53], v[52:53], v[230:231], v[24:25]

.LBB0_690:
	s_or_b64 exec, exec, s[4:5]
	s_waitcnt vmcnt(2) lgkmcnt(0)
	s_nop 0
	v_permlane32_swap_b32_e32 v199, v200
	v_add_f32_e32 v32, v199, v200
	v_fmamk_f32 v32, v32, 0x3a800000, v195
	v_rsq_f32_e32 v32, v32
	s_nop 0
	v_pk_mul_f32 v[14:15], v[14:15], v[32:33] op_sel_hi:[1,0]
	v_pk_mul_f32 v[12:13], v[12:13], v[32:33] op_sel_hi:[1,0]
	v_pk_mul_f32 v[34:35], v[10:11], v[32:33] op_sel_hi:[1,0]
	s_and_b64 vcc, exec, s[12:13]
	v_pk_mul_f32 v[36:37], v[8:9], v[32:33] op_sel_hi:[1,0]
	s_cbranch_vccnz .LBB0_692
	ds_bpermute_b32 v8, v198, v12
	ds_bpermute_b32 v9, v198, v13
	ds_bpermute_b32 v10, v198, v36
	ds_bpermute_b32 v38, v198, v14
	ds_bpermute_b32 v39, v198, v15
	ds_bpermute_b32 v11, v198, v37
	ds_bpermute_b32 v40, v198, v34
	ds_bpermute_b32 v41, v198, v35
	s_waitcnt lgkmcnt(6)
	v_pk_mul_f32 v[8:9], v[28:29], v[8:9]
	s_waitcnt lgkmcnt(3)
	v_pk_mul_f32 v[38:39], v[30:31], v[38:39]
	s_waitcnt vmcnt(1)
	v_pk_fma_f32 v[12:13], v[12:13], v[242:243], v[8:9]
	s_waitcnt lgkmcnt(2)
	v_pk_mul_f32 v[8:9], v[26:27], v[10:11]
	s_waitcnt lgkmcnt(0)
	v_pk_mul_f32 v[10:11], v[24:25], v[40:41]
	v_pk_fma_f32 v[14:15], v[14:15], v[244:245], v[38:39]
	s_waitcnt vmcnt(0)
	v_pk_fma_f32 v[34:35], v[34:35], v[248:249], v[10:11]
	v_pk_fma_f32 v[36:37], v[36:37], v[246:247], v[8:9]

.LBB0_1051:
	v_lshl_add_u32 v162, s8, 8, v159
	s_cmp_eq_u32 s8, s62
	s_cbranch_scc1 .Lrstd_reuse_p9
	s_mov_b64 s[60:61], 0x2000
	v_lshlrev_b32_e32 v204, 6, v162
	v_mov_b32_e32 v205, 0
	v_mbcnt_lo_u32_b32 v248, -1, 0
	v_mbcnt_hi_u32_b32 v248, -1, v248
	v_xor_b32_e32 v248, 16, v248
	v_lshl_add_u64 v[204:205], v[136:137], 0, v[204:205]
	v_lshlrev_b32_e32 v248, 2, v248
	v_lshl_add_u64 v[206:207], v[204:205], 0, s[60:61]
	global_load_dwordx4 v[208:211], v[204:205], off
	global_load_dwordx4 v[212:215], v[204:205], off offset:1024
	global_load_dwordx4 v[216:219], v[204:205], off offset:2048
	global_load_dwordx4 v[220:223], v[204:205], off offset:3072
	global_load_dwordx4 v[224:227], v[206:207], off
	global_load_dwordx4 v[228:231], v[206:207], off offset:1024
	global_load_dwordx4 v[232:235], v[206:207], off offset:2048
	global_load_dwordx4 v[236:239], v[206:207], off offset:3072
	s_waitcnt vmcnt(0)
	v_add_f32_e32 v208, v208, v209
	v_add_f32_e32 v210, v210, v211
	v_add_f32_e32 v212, v212, v213
	v_add_f32_e32 v214, v214, v215
	v_add_f32_e32 v216, v216, v217
	v_add_f32_e32 v218, v218, v219
	v_add_f32_e32 v220, v220, v221
	v_add_f32_e32 v222, v222, v223
	v_add_f32_e32 v224, v224, v225
	v_add_f32_e32 v226, v226, v227
	v_add_f32_e32 v228, v228, v229
	v_add_f32_e32 v230, v230, v231
	v_add_f32_e32 v232, v232, v233
	v_add_f32_e32 v234, v234, v235
	v_add_f32_e32 v236, v236, v237
	v_add_f32_e32 v238, v238, v239
	v_add_f32_e32 v208, v208, v210
	v_add_f32_e32 v212, v212, v214
	v_add_f32_e32 v216, v216, v218
	v_add_f32_e32 v220, v220, v222
	v_add_f32_e32 v224, v224, v226
	v_add_f32_e32 v228, v228, v230
	v_add_f32_e32 v232, v232, v234
	v_add_f32_e32 v236, v236, v238
	v_mov_b32_e32 v209, v208
	v_mov_b32_e32 v213, v212
	v_mov_b32_e32 v217, v216
	v_mov_b32_e32 v221, v220
	v_mov_b32_e32 v225, v224
	v_mov_b32_e32 v229, v228
	v_mov_b32_e32 v233, v232
	v_mov_b32_e32 v237, v236
	s_waitcnt lgkmcnt(0)
	v_permlane16_swap_b32_e32 v208, v209
	v_add_f32_e32 v208, v208, v209
	v_permlane16_swap_b32_e32 v212, v213
	v_add_f32_e32 v212, v212, v213
	v_permlane16_swap_b32_e32 v216, v217
	v_add_f32_e32 v216, v216, v217
	v_permlane16_swap_b32_e32 v220, v221
	v_add_f32_e32 v220, v220, v221
	v_permlane16_swap_b32_e32 v224, v225
	v_add_f32_e32 v224, v224, v225
	v_permlane16_swap_b32_e32 v228, v229
	v_add_f32_e32 v228, v228, v229
	v_permlane16_swap_b32_e32 v232, v233
	v_add_f32_e32 v232, v232, v233
	v_permlane16_swap_b32_e32 v236, v237
	v_add_f32_e32 v236, v236, v237
	v_mov_b32_e32 v209, v208
	v_mov_b32_e32 v213, v212
	v_mov_b32_e32 v217, v216
	v_mov_b32_e32 v221, v220
	v_mov_b32_e32 v225, v224
	v_mov_b32_e32 v229, v228
	v_mov_b32_e32 v233, v232
	v_mov_b32_e32 v237, v236
	s_nop 1
	v_permlane32_swap_b32_e32 v208, v209
	v_permlane32_swap_b32_e32 v212, v213
	v_permlane32_swap_b32_e32 v216, v217
	v_permlane32_swap_b32_e32 v220, v221
	v_permlane32_swap_b32_e32 v224, v225
	v_permlane32_swap_b32_e32 v228, v229
	v_permlane32_swap_b32_e32 v232, v233
	v_permlane32_swap_b32_e32 v236, v237
	v_add_f32_e32 v208, v208, v209
	v_add_f32_e32 v212, v212, v213
	v_add_f32_e32 v216, v216, v217
	v_add_f32_e32 v220, v220, v221
	v_add_f32_e32 v224, v224, v225
	v_add_f32_e32 v228, v228, v229
	v_add_f32_e32 v232, v232, v233
	v_add_f32_e32 v236, v236, v237
	v_fmamk_f32 v208, v208, 0x3a800000, v175
	v_fmamk_f32 v212, v212, 0x3a800000, v175
	v_fmamk_f32 v216, v216, 0x3a800000, v175
	v_fmamk_f32 v220, v220, 0x3a800000, v175
	v_fmamk_f32 v224, v224, 0x3a800000, v175
	v_fmamk_f32 v228, v228, 0x3a800000, v175
	v_fmamk_f32 v232, v232, 0x3a800000, v175
	v_fmamk_f32 v236, v236, 0x3a800000, v175
	v_rsq_f32_e32 v176, v208
	v_rsq_f32_e32 v174, v212
	v_rsq_f32_e32 v172, v216
	v_rsq_f32_e32 v170, v220
	v_rsq_f32_e32 v168, v224
	v_rsq_f32_e32 v166, v228
	v_rsq_f32_e32 v164, v232
	v_rsq_f32_e32 v158, v236
	s_nop 0
	v_mov_b32_e32 v240, v176
	v_mov_b32_e32 v241, v174
	v_mov_b32_e32 v242, v172
	v_mov_b32_e32 v243, v170
	v_mov_b32_e32 v244, v168
	v_mov_b32_e32 v245, v166
	v_mov_b32_e32 v246, v164
	v_mov_b32_e32 v247, v158
	s_mov_b32 s62, s8
	s_branch .Lrstd_done_p9
